# GEMM K=1024 main loops: counted lgkmcnt waits, LDS-DMA issue spread between MFMA groups, second-half A reads issued early
# speedup vs baseline: 1.0183x; 1.0183x over previous
.LBB0_204:
	s_add_i32 s9, s8, 0xfffe8000
	s_and_b32 s10, s8, 0x18000
	s_waitcnt vmcnt(8)
	s_barrier
	s_and_b32 s9, s9, 0x18000
	s_add_i32 s10, s7, s10
	v_add_u32_e32 v112, s9, v135
	v_or_b32_e32 v139, s9, v137
	s_add_i32 s18, s10, 0x400
	s_add_i32 s11, s10, 0x800
	s_add_i32 s9, s10, 0xc00
	s_add_i32 s8, s8, 0x8000
	s_cmp_eq_u32 s8, 0x100000
	ds_read_b128 v[186:189], v112
	ds_read_b128 v[158:161], v139
	ds_read_b128 v[162:165], v139 offset:1024
	ds_read_b128 v[166:169], v139 offset:2048
	ds_read_b128 v[182:185], v139 offset:3072
	ds_read_b128 v[190:193], v112 offset:1024
	ds_read_b128 v[194:197], v112 offset:2048
	ds_read_b128 v[198:201], v112 offset:3072
	s_waitcnt lgkmcnt(6)
	v_mfma_f32_16x16x32_bf16 v[126:129], v[158:161], v[186:189], v[126:129]
	s_waitcnt lgkmcnt(5)
	v_mfma_f32_16x16x32_bf16 v[122:125], v[162:165], v[186:189], v[122:125]
	s_waitcnt lgkmcnt(4)
	v_mfma_f32_16x16x32_bf16 v[118:121], v[166:169], v[186:189], v[118:121]
	s_waitcnt lgkmcnt(3)
	s_mov_b32 m0, s10
	v_mfma_f32_16x16x32_bf16 v[114:117], v[182:185], v[186:189], v[114:117]
	global_load_lds_dwordx4 v[154:155], off
	v_lshl_add_u64 v[154:155], v[154:155], 0, 64
	s_waitcnt lgkmcnt(2)
	v_mfma_f32_16x16x32_bf16 v[108:111], v[158:161], v[190:193], v[108:111]
	ds_read_b128 v[186:189], v112 offset:4096
	v_mfma_f32_16x16x32_bf16 v[104:107], v[162:165], v[190:193], v[104:107]
	v_mfma_f32_16x16x32_bf16 v[100:103], v[166:169], v[190:193], v[100:103]
	s_mov_b32 m0, s18
	v_mfma_f32_16x16x32_bf16 v[96:99], v[182:185], v[190:193], v[96:99]
	global_load_lds_dwordx4 v[152:153], off
	v_lshl_add_u64 v[152:153], v[152:153], 0, 64
	s_waitcnt lgkmcnt(2)
	v_mfma_f32_16x16x32_bf16 v[92:95], v[158:161], v[194:197], v[92:95]
	ds_read_b128 v[190:193], v112 offset:5120
	v_mfma_f32_16x16x32_bf16 v[88:91], v[162:165], v[194:197], v[88:91]
	v_mfma_f32_16x16x32_bf16 v[84:87], v[166:169], v[194:197], v[84:87]
	s_mov_b32 m0, s11
	v_mfma_f32_16x16x32_bf16 v[80:83], v[182:185], v[194:197], v[80:83]
	global_load_lds_dwordx4 v[150:151], off
	v_lshl_add_u64 v[150:151], v[150:151], 0, 64
	s_waitcnt lgkmcnt(2)
	v_mfma_f32_16x16x32_bf16 v[76:79], v[158:161], v[198:201], v[76:79]
	ds_read_b128 v[194:197], v112 offset:6144
	v_mfma_f32_16x16x32_bf16 v[72:75], v[162:165], v[198:201], v[72:75]
	v_mfma_f32_16x16x32_bf16 v[68:71], v[166:169], v[198:201], v[68:71]
	s_mov_b32 m0, s9
	v_mfma_f32_16x16x32_bf16 v[64:67], v[182:185], v[198:201], v[64:67]
	global_load_lds_dwordx4 v[148:149], off
	v_lshl_add_u64 v[148:149], v[148:149], 0, 64
	s_waitcnt lgkmcnt(2)
	v_mfma_f32_16x16x32_bf16 v[60:63], v[158:161], v[186:189], v[60:63]
	ds_read_b128 v[198:201], v112 offset:7168
	v_mfma_f32_16x16x32_bf16 v[56:59], v[162:165], v[186:189], v[56:59]
	v_mfma_f32_16x16x32_bf16 v[52:55], v[166:169], v[186:189], v[52:55]
	v_mfma_f32_16x16x32_bf16 v[48:51], v[182:185], v[186:189], v[48:51]
	s_waitcnt lgkmcnt(2)
	v_mfma_f32_16x16x32_bf16 v[44:47], v[158:161], v[190:193], v[44:47]
	v_mfma_f32_16x16x32_bf16 v[40:43], v[162:165], v[190:193], v[40:43]
	v_mfma_f32_16x16x32_bf16 v[36:39], v[166:169], v[190:193], v[36:39]
	v_mfma_f32_16x16x32_bf16 v[32:35], v[182:185], v[190:193], v[32:35]
	s_waitcnt lgkmcnt(1)
	v_mfma_f32_16x16x32_bf16 v[28:31], v[158:161], v[194:197], v[28:31]
	v_mfma_f32_16x16x32_bf16 v[24:27], v[162:165], v[194:197], v[24:27]
	v_mfma_f32_16x16x32_bf16 v[20:23], v[166:169], v[194:197], v[20:23]
	v_mfma_f32_16x16x32_bf16 v[16:19], v[182:185], v[194:197], v[16:19]
	s_waitcnt lgkmcnt(0)
	v_mfma_f32_16x16x32_bf16 v[12:15], v[158:161], v[198:201], v[12:15]
	v_mfma_f32_16x16x32_bf16 v[8:11], v[162:165], v[198:201], v[8:11]
	v_mfma_f32_16x16x32_bf16 v[4:7], v[166:169], v[198:201], v[4:7]
	v_mfma_f32_16x16x32_bf16 v[0:3], v[182:185], v[198:201], v[0:3]
	s_cbranch_scc0 .LBB0_204
	s_waitcnt vmcnt(8)
	s_barrier
	v_add_u32_e32 v112, 0x8000, v135
	v_or_b32_e32 v139, 0x8000, v137
	ds_read_b128 v[148:151], v139
	ds_read_b128 v[152:155], v139 offset:1024
	ds_read_b128 v[158:161], v139 offset:2048
	ds_read_b128 v[162:165], v139 offset:3072
	ds_read_b128 v[166:169], v112
	ds_read_b128 v[182:185], v112 offset:1024
	ds_read_b128 v[186:189], v112 offset:2048
	ds_read_b128 v[190:193], v112 offset:3072
	v_or_b32_e32 v139, 0x10000, v137
	s_waitcnt lgkmcnt(0)
	s_lshl_b32 s7, s4, 8
	v_mfma_f32_16x16x32_bf16 v[126:129], v[148:151], v[166:169], v[126:129]
	s_and_b32 s4, s4, 0xc0
	s_and_b32 s78, s7, 0xffffc000
	s_or_b32 s8, s5, s4
	v_mfma_f32_16x16x32_bf16 v[122:125], v[152:155], v[166:169], v[122:125]
	s_mov_b64 s[4:5], -1
	s_cmpk_gt_i32 s8, 0x17f
	v_mfma_f32_16x16x32_bf16 v[118:121], v[158:161], v[166:169], v[118:121]
	v_mfma_f32_16x16x32_bf16 v[114:117], v[162:165], v[166:169], v[114:117]
	v_mfma_f32_16x16x32_bf16 v[108:111], v[148:151], v[182:185], v[108:111]
	v_mfma_f32_16x16x32_bf16 v[104:107], v[152:155], v[182:185], v[104:107]
	v_mfma_f32_16x16x32_bf16 v[100:103], v[158:161], v[182:185], v[100:103]
	v_mfma_f32_16x16x32_bf16 v[96:99], v[162:165], v[182:185], v[96:99]
	v_mfma_f32_16x16x32_bf16 v[92:95], v[148:151], v[186:189], v[92:95]
	v_mfma_f32_16x16x32_bf16 v[88:91], v[152:155], v[186:189], v[88:91]
	v_mfma_f32_16x16x32_bf16 v[84:87], v[158:161], v[186:189], v[84:87]
	v_mfma_f32_16x16x32_bf16 v[80:83], v[162:165], v[186:189], v[80:83]
	v_mfma_f32_16x16x32_bf16 v[76:79], v[148:151], v[190:193], v[76:79]
	v_mfma_f32_16x16x32_bf16 v[72:75], v[152:155], v[190:193], v[72:75]
	v_mfma_f32_16x16x32_bf16 v[68:71], v[158:161], v[190:193], v[68:71]
	v_mfma_f32_16x16x32_bf16 v[64:67], v[162:165], v[190:193], v[64:67]
	ds_read_b128 v[166:169], v112 offset:4096
	ds_read_b128 v[182:185], v112 offset:5120
	ds_read_b128 v[186:189], v112 offset:6144
	ds_read_b128 v[190:193], v112 offset:7168
	s_waitcnt lgkmcnt(0)
	s_waitcnt vmcnt(4)
	s_barrier
	v_mfma_f32_16x16x32_bf16 v[60:63], v[148:151], v[166:169], v[60:63]
	v_add_u32_e32 v112, 0x10000, v135
	v_mfma_f32_16x16x32_bf16 v[56:59], v[152:155], v[166:169], v[56:59]
	v_mfma_f32_16x16x32_bf16 v[52:55], v[158:161], v[166:169], v[52:55]
	v_mfma_f32_16x16x32_bf16 v[48:51], v[162:165], v[166:169], v[48:51]
	v_mfma_f32_16x16x32_bf16 v[44:47], v[148:151], v[182:185], v[44:47]
	v_mfma_f32_16x16x32_bf16 v[40:43], v[152:155], v[182:185], v[40:43]
	v_mfma_f32_16x16x32_bf16 v[36:39], v[158:161], v[182:185], v[36:39]
	v_mfma_f32_16x16x32_bf16 v[32:35], v[162:165], v[182:185], v[32:35]
	v_mfma_f32_16x16x32_bf16 v[28:31], v[148:151], v[186:189], v[28:31]
	v_mfma_f32_16x16x32_bf16 v[24:27], v[152:155], v[186:189], v[24:27]
	v_mfma_f32_16x16x32_bf16 v[20:23], v[158:161], v[186:189], v[20:23]
	v_mfma_f32_16x16x32_bf16 v[16:19], v[162:165], v[186:189], v[16:19]
	v_mfma_f32_16x16x32_bf16 v[12:15], v[148:151], v[190:193], v[12:15]
	v_mfma_f32_16x16x32_bf16 v[8:11], v[152:155], v[190:193], v[8:11]
	v_mfma_f32_16x16x32_bf16 v[4:7], v[158:161], v[190:193], v[4:7]
	v_mfma_f32_16x16x32_bf16 v[0:3], v[162:165], v[190:193], v[0:3]
	ds_read_b128 v[148:151], v139
	ds_read_b128 v[152:155], v139 offset:1024
	ds_read_b128 v[158:161], v139 offset:2048
	ds_read_b128 v[162:165], v139 offset:3072
	ds_read_b128 v[166:169], v112
	ds_read_b128 v[182:185], v112 offset:1024
	ds_read_b128 v[186:189], v112 offset:2048
	ds_read_b128 v[190:193], v112 offset:3072
	s_nop 0
	s_waitcnt lgkmcnt(0)
	s_nop 0
	v_mfma_f32_16x16x32_bf16 v[126:129], v[148:151], v[166:169], v[126:129]
	v_mfma_f32_16x16x32_bf16 v[122:125], v[152:155], v[166:169], v[122:125]
	v_mfma_f32_16x16x32_bf16 v[118:121], v[158:161], v[166:169], v[118:121]
	v_mfma_f32_16x16x32_bf16 v[114:117], v[162:165], v[166:169], v[114:117]
	v_mfma_f32_16x16x32_bf16 v[108:111], v[148:151], v[182:185], v[108:111]
	v_mfma_f32_16x16x32_bf16 v[104:107], v[152:155], v[182:185], v[104:107]
	v_mfma_f32_16x16x32_bf16 v[100:103], v[158:161], v[182:185], v[100:103]
	v_mfma_f32_16x16x32_bf16 v[96:99], v[162:165], v[182:185], v[96:99]
	v_mfma_f32_16x16x32_bf16 v[92:95], v[148:151], v[186:189], v[92:95]
	v_mfma_f32_16x16x32_bf16 v[88:91], v[152:155], v[186:189], v[88:91]
	v_mfma_f32_16x16x32_bf16 v[84:87], v[158:161], v[186:189], v[84:87]
	v_mfma_f32_16x16x32_bf16 v[80:83], v[162:165], v[186:189], v[80:83]
	v_mfma_f32_16x16x32_bf16 v[76:79], v[148:151], v[190:193], v[76:79]
	v_mfma_f32_16x16x32_bf16 v[72:75], v[152:155], v[190:193], v[72:75]
	v_mfma_f32_16x16x32_bf16 v[68:71], v[158:161], v[190:193], v[68:71]
	v_mfma_f32_16x16x32_bf16 v[64:67], v[162:165], v[190:193], v[64:67]
	ds_read_b128 v[166:169], v112 offset:4096
	ds_read_b128 v[182:185], v112 offset:5120
	ds_read_b128 v[186:189], v112 offset:6144
	ds_read_b128 v[190:193], v112 offset:7168
	s_waitcnt lgkmcnt(0)
	s_waitcnt vmcnt(0)
	s_barrier
	v_mfma_f32_16x16x32_bf16 v[60:63], v[148:151], v[166:169], v[60:63]
	v_add_u32_e32 v112, 0x18000, v135
	v_or_b32_e32 v135, 0x18000, v137
	v_mfma_f32_16x16x32_bf16 v[56:59], v[152:155], v[166:169], v[56:59]
	v_bfe_u32 v137, v131, 4, 2
	v_mfma_f32_16x16x32_bf16 v[52:55], v[158:161], v[166:169], v[52:55]
	v_mfma_f32_16x16x32_bf16 v[48:51], v[162:165], v[166:169], v[48:51]
	v_mfma_f32_16x16x32_bf16 v[44:47], v[148:151], v[182:185], v[44:47]
	v_mfma_f32_16x16x32_bf16 v[40:43], v[152:155], v[182:185], v[40:43]
	v_mfma_f32_16x16x32_bf16 v[36:39], v[158:161], v[182:185], v[36:39]
	v_mfma_f32_16x16x32_bf16 v[32:35], v[162:165], v[182:185], v[32:35]
	v_mfma_f32_16x16x32_bf16 v[28:31], v[148:151], v[186:189], v[28:31]
	v_mfma_f32_16x16x32_bf16 v[24:27], v[152:155], v[186:189], v[24:27]
	v_mfma_f32_16x16x32_bf16 v[20:23], v[158:161], v[186:189], v[20:23]
	v_mfma_f32_16x16x32_bf16 v[16:19], v[162:165], v[186:189], v[16:19]
	v_mfma_f32_16x16x32_bf16 v[12:15], v[148:151], v[190:193], v[12:15]
	v_mfma_f32_16x16x32_bf16 v[8:11], v[152:155], v[190:193], v[8:11]
	v_mfma_f32_16x16x32_bf16 v[4:7], v[158:161], v[190:193], v[4:7]
	v_mfma_f32_16x16x32_bf16 v[0:3], v[162:165], v[190:193], v[0:3]
	ds_read_b128 v[164:167], v135
	ds_read_b128 v[168:171], v135 offset:1024
	ds_read_b128 v[182:185], v135 offset:2048
	ds_read_b128 v[186:189], v135 offset:3072
	ds_read_b128 v[148:151], v112
	ds_read_b128 v[152:155], v112 offset:1024
	ds_read_b128 v[158:161], v112 offset:2048
	ds_read_b128 v[190:193], v112 offset:3072
	v_or_b32_e32 v162, 16, v144
	s_waitcnt lgkmcnt(0)
	v_ashrrev_i32_e32 v163, 31, v162
	v_mfma_f32_16x16x32_bf16 v[126:129], v[164:167], v[148:151], v[126:129]
	v_and_b32_e32 v135, 63, v131
	v_mfma_f32_16x16x32_bf16 v[122:125], v[168:171], v[148:151], v[122:125]
	v_mfma_f32_16x16x32_bf16 v[118:121], v[182:185], v[148:151], v[118:121]
	v_mfma_f32_16x16x32_bf16 v[114:117], v[186:189], v[148:151], v[114:117]
	v_mfma_f32_16x16x32_bf16 v[108:111], v[164:167], v[152:155], v[108:111]
	v_mfma_f32_16x16x32_bf16 v[104:107], v[168:171], v[152:155], v[104:107]
	v_mfma_f32_16x16x32_bf16 v[100:103], v[182:185], v[152:155], v[100:103]
	v_mfma_f32_16x16x32_bf16 v[96:99], v[186:189], v[152:155], v[96:99]
	v_mfma_f32_16x16x32_bf16 v[92:95], v[164:167], v[158:161], v[92:95]
	v_mfma_f32_16x16x32_bf16 v[88:91], v[168:171], v[158:161], v[88:91]
	v_mfma_f32_16x16x32_bf16 v[84:87], v[182:185], v[158:161], v[84:87]
	v_mfma_f32_16x16x32_bf16 v[80:83], v[186:189], v[158:161], v[80:83]
	v_or_b32_e32 v160, 32, v144
	v_or_b32_e32 v158, 48, v144
	v_ashrrev_i32_e32 v161, 31, v160
	v_mfma_f32_16x16x32_bf16 v[76:79], v[164:167], v[190:193], v[76:79]
	v_ashrrev_i32_e32 v159, 31, v158
	v_mfma_f32_16x16x32_bf16 v[72:75], v[168:171], v[190:193], v[72:75]
	v_mfma_f32_16x16x32_bf16 v[68:71], v[182:185], v[190:193], v[68:71]
	v_mfma_f32_16x16x32_bf16 v[64:67], v[186:189], v[190:193], v[64:67]
	ds_read_b128 v[148:151], v112 offset:4096
	ds_read_b128 v[152:155], v112 offset:5120
	ds_read_b128 v[190:193], v112 offset:6144
	ds_read_b128 v[194:197], v112 offset:7168
	s_waitcnt lgkmcnt(0)
	s_barrier
	v_mfma_f32_16x16x32_bf16 v[60:63], v[164:167], v[148:151], v[60:63]
	v_mfma_f32_16x16x32_bf16 v[56:59], v[168:171], v[148:151], v[56:59]
	v_mfma_f32_16x16x32_bf16 v[52:55], v[182:185], v[148:151], v[52:55]
	v_mfma_f32_16x16x32_bf16 v[48:51], v[186:189], v[148:151], v[48:51]
	v_or_b32_e32 v150, 0x60, v144
	v_or_b32_e32 v148, 0x70, v144
	v_ashrrev_i32_e32 v151, 31, v150
	v_mfma_f32_16x16x32_bf16 v[44:47], v[164:167], v[152:155], v[44:47]
	v_ashrrev_i32_e32 v149, 31, v148
	v_mfma_f32_16x16x32_bf16 v[40:43], v[168:171], v[152:155], v[40:43]
	v_mfma_f32_16x16x32_bf16 v[36:39], v[182:185], v[152:155], v[36:39]
	v_mfma_f32_16x16x32_bf16 v[32:35], v[186:189], v[152:155], v[32:35]
	v_or_b32_e32 v154, 64, v144
	v_or_b32_e32 v152, 0x50, v144
	v_ashrrev_i32_e32 v155, 31, v154
	v_mfma_f32_16x16x32_bf16 v[28:31], v[164:167], v[190:193], v[28:31]
	v_ashrrev_i32_e32 v153, 31, v152
	v_mfma_f32_16x16x32_bf16 v[24:27], v[168:171], v[190:193], v[24:27]
	v_mfma_f32_16x16x32_bf16 v[20:23], v[182:185], v[190:193], v[20:23]
	v_mfma_f32_16x16x32_bf16 v[16:19], v[186:189], v[190:193], v[16:19]
	v_mfma_f32_16x16x32_bf16 v[12:15], v[164:167], v[194:197], v[12:15]
	v_mfma_f32_16x16x32_bf16 v[8:11], v[168:171], v[194:197], v[8:11]
	v_mfma_f32_16x16x32_bf16 v[4:7], v[182:185], v[194:197], v[4:7]
	v_mfma_f32_16x16x32_bf16 v[0:3], v[186:189], v[194:197], v[0:3]
	s_cbranch_scc0 .LBB0_213
	s_cmpk_gt_u32 s8, 0x57f
	s_cbranch_scc0 .LBB0_210
	s_cmpk_lg_i32 s8, 0x580
	s_cbranch_scc1 .LBB0_209
	v_lshlrev_b32_e32 v112, 7, v144
	v_and_b32_e32 v112, 0x7c780, v112
	v_lshl_add_u64 v[164:165], s[46:47], 0, v[112:113]
	v_lshlrev_b32_e32 v112, 5, v137
	v_lshl_add_u64 v[168:169], v[164:165], 0, v[112:113]
	global_load_dwordx4 v[164:167], v[168:169], off offset:16
	s_nop 0
	global_load_dwordx4 v[168:171], v[168:169], off
	v_pk_mul_f32 v[184:185], v[146:147], v[122:123] op_sel_hi:[0,1]
	v_pk_mul_f32 v[176:177], v[146:147], v[126:127] op_sel_hi:[0,1]
	v_pk_mul_f32 v[182:183], v[146:147], v[124:125] op_sel_hi:[0,1]
	v_pk_mul_f32 v[174:175], v[146:147], v[128:129] op_sel_hi:[0,1]
	v_lshlrev_b32_e32 v139, 7, v162
	s_waitcnt vmcnt(0)
	v_mov_b32_e32 v186, v168
	v_mov_b32_e32 v187, v170
	v_mov_b32_e32 v170, v169
	v_pk_mul_f32 v[168:169], v[184:185], v[170:171]
	v_pk_mul_f32 v[184:185], v[184:185], v[186:187]
	v_pk_fma_f32 v[168:169], v[176:177], v[186:187], v[168:169] neg_lo:[0,0,1] neg_hi:[0,0,1]
	v_pk_fma_f32 v[170:171], v[176:177], v[170:171], v[184:185]
	v_mov_b32_e32 v177, v166
	v_mov_b32_e32 v166, v165
	v_mov_b32_e32 v176, v164
	v_pk_mul_f32 v[164:165], v[182:183], v[166:167]
	v_cvt_pk_bf16_f32 v168, v168, v169
	v_pk_fma_f32 v[164:165], v[174:175], v[176:177], v[164:165] neg_lo:[0,0,1] neg_hi:[0,0,1]
	v_pk_mul_f32 v[176:177], v[182:183], v[176:177]
	v_cvt_pk_bf16_f32 v169, v164, v165
	v_lshlrev_b64 v[164:165], 6, v[144:145]
	v_pk_fma_f32 v[166:167], v[174:175], v[166:167], v[176:177]
	v_lshl_add_u64 v[174:175], s[36:37], 0, v[164:165]
	v_lshlrev_b32_e32 v164, 3, v137
	v_mov_b32_e32 v165, v113
	v_lshl_add_u64 v[174:175], v[174:175], 0, v[164:165]
	global_store_dwordx2 v[174:175], v[168:169], off
	v_cvt_pk_bf16_f32 v169, v166, v167
	v_and_b32_e32 v166, 0x7cf80, v139
	v_mov_b32_e32 v167, v113
	v_cvt_pk_bf16_f32 v168, v170, v171
	v_lshl_add_u64 v[166:167], s[46:47], 0, v[166:167]
	global_store_dwordx2 v[174:175], v[168:169], off offset:32
	v_lshl_add_u64 v[182:183], v[166:167], 0, v[112:113]
	global_load_dwordx4 v[166:169], v[182:183], off offset:16
	s_nop 0
	global_load_dwordx4 v[182:185], v[182:183], off
	v_pk_mul_f32 v[186:187], v[142:143], v[104:105] op_sel_hi:[0,1]
	v_pk_mul_f32 v[174:175], v[142:143], v[108:109] op_sel_hi:[0,1]
	v_pk_mul_f32 v[176:177], v[142:143], v[106:107] op_sel_hi:[0,1]
	v_pk_mul_f32 v[170:171], v[142:143], v[110:111] op_sel_hi:[0,1]
	v_lshlrev_b32_e32 v139, 7, v160
	s_waitcnt vmcnt(0)
	v_mov_b32_e32 v188, v182
	v_mov_b32_e32 v189, v184
	v_mov_b32_e32 v184, v183
	v_pk_mul_f32 v[182:183], v[186:187], v[184:185]
	v_pk_mul_f32 v[186:187], v[186:187], v[188:189]
	v_pk_fma_f32 v[182:183], v[174:175], v[188:189], v[182:183] neg_lo:[0,0,1] neg_hi:[0,0,1]
	v_pk_fma_f32 v[174:175], v[174:175], v[184:185], v[186:187]
	v_mov_b32_e32 v185, v168
	v_mov_b32_e32 v168, v167
	v_mov_b32_e32 v184, v166
	v_pk_mul_f32 v[166:167], v[176:177], v[168:169]
	v_pk_mul_f32 v[176:177], v[176:177], v[184:185]
	v_pk_fma_f32 v[166:167], v[170:171], v[184:185], v[166:167] neg_lo:[0,0,1] neg_hi:[0,0,1]
	v_pk_fma_f32 v[168:169], v[170:171], v[168:169], v[176:177]
	v_cvt_pk_bf16_f32 v171, v166, v167
	v_lshlrev_b64 v[166:167], 6, v[162:163]
	v_lshl_add_u64 v[166:167], s[36:37], 0, v[166:167]
	v_cvt_pk_bf16_f32 v170, v182, v183
	v_lshl_add_u64 v[166:167], v[166:167], 0, v[164:165]
	global_store_dwordx2 v[166:167], v[170:171], off
	v_cvt_pk_bf16_f32 v170, v174, v175
	v_cvt_pk_bf16_f32 v171, v168, v169
	global_store_dwordx2 v[166:167], v[170:171], off offset:32
	v_and_b32_e32 v166, 0x7d780, v139
	v_mov_b32_e32 v167, v113
	v_lshl_add_u64 v[166:167], s[46:47], 0, v[166:167]
	v_lshl_add_u64 v[182:183], v[166:167], 0, v[112:113]
	global_load_dwordx4 v[166:169], v[182:183], off offset:16
	s_nop 0
	global_load_dwordx4 v[182:185], v[182:183], off
	v_pk_mul_f32 v[186:187], v[140:141], v[88:89] op_sel_hi:[0,1]
	v_pk_mul_f32 v[174:175], v[140:141], v[92:93] op_sel_hi:[0,1]
	v_pk_mul_f32 v[176:177], v[140:141], v[90:91] op_sel_hi:[0,1]
	v_pk_mul_f32 v[170:171], v[140:141], v[94:95] op_sel_hi:[0,1]
	s_waitcnt vmcnt(0)
	v_mov_b32_e32 v188, v182
	v_mov_b32_e32 v189, v184
	v_mov_b32_e32 v184, v183
	v_pk_mul_f32 v[182:183], v[186:187], v[184:185]
	v_pk_mul_f32 v[186:187], v[186:187], v[188:189]
	v_pk_fma_f32 v[182:183], v[174:175], v[188:189], v[182:183] neg_lo:[0,0,1] neg_hi:[0,0,1]
	v_pk_fma_f32 v[174:175], v[174:175], v[184:185], v[186:187]
	v_mov_b32_e32 v185, v168
	v_mov_b32_e32 v168, v167
	v_mov_b32_e32 v184, v166
	v_pk_mul_f32 v[166:167], v[176:177], v[168:169]
	v_pk_mul_f32 v[176:177], v[176:177], v[184:185]
	v_pk_fma_f32 v[166:167], v[170:171], v[184:185], v[166:167] neg_lo:[0,0,1] neg_hi:[0,0,1]
	v_pk_fma_f32 v[168:169], v[170:171], v[168:169], v[176:177]
	v_cvt_pk_bf16_f32 v171, v166, v167
	v_lshlrev_b64 v[166:167], 6, v[160:161]
	v_lshl_add_u64 v[166:167], s[36:37], 0, v[166:167]
	v_cvt_pk_bf16_f32 v170, v182, v183
	v_lshl_add_u64 v[166:167], v[166:167], 0, v[164:165]
	global_store_dwordx2 v[166:167], v[170:171], off
	v_cvt_pk_bf16_f32 v170, v174, v175
	v_cvt_pk_bf16_f32 v171, v168, v169
	global_store_dwordx2 v[166:167], v[170:171], off offset:32
	v_pk_mul_f32 v[170:171], v[138:139], v[78:79] op_sel_hi:[0,1]
	v_pk_mul_f32 v[174:175], v[138:139], v[76:77] op_sel_hi:[0,1]
	v_pk_mul_f32 v[176:177], v[138:139], v[74:75] op_sel_hi:[0,1]
	v_pk_mul_f32 v[186:187], v[138:139], v[72:73] op_sel_hi:[0,1]
	v_lshlrev_b32_e32 v139, 7, v158
	v_and_b32_e32 v166, 0x7df80, v139
	v_mov_b32_e32 v167, v113
	v_lshl_add_u64 v[166:167], s[46:47], 0, v[166:167]
	v_lshl_add_u64 v[182:183], v[166:167], 0, v[112:113]
	global_load_dwordx4 v[166:169], v[182:183], off offset:16
	s_nop 0
	global_load_dwordx4 v[182:185], v[182:183], off
	v_lshlrev_b32_e32 v139, 7, v154
	s_waitcnt vmcnt(0)
	v_mov_b32_e32 v188, v182
	v_mov_b32_e32 v189, v184
	v_mov_b32_e32 v184, v183
	v_pk_mul_f32 v[182:183], v[186:187], v[184:185]
	v_pk_mul_f32 v[186:187], v[186:187], v[188:189]
	v_pk_fma_f32 v[182:183], v[174:175], v[188:189], v[182:183] neg_lo:[0,0,1] neg_hi:[0,0,1]
	v_pk_fma_f32 v[174:175], v[174:175], v[184:185], v[186:187]
	v_mov_b32_e32 v185, v168
	v_mov_b32_e32 v168, v167
	v_mov_b32_e32 v184, v166
	v_pk_mul_f32 v[166:167], v[176:177], v[168:169]
	v_pk_mul_f32 v[176:177], v[176:177], v[184:185]
	v_pk_fma_f32 v[166:167], v[170:171], v[184:185], v[166:167] neg_lo:[0,0,1] neg_hi:[0,0,1]
	v_pk_fma_f32 v[168:169], v[170:171], v[168:169], v[176:177]
	v_cvt_pk_bf16_f32 v171, v166, v167
	v_lshlrev_b64 v[166:167], 6, v[158:159]
	v_lshl_add_u64 v[166:167], s[36:37], 0, v[166:167]
	v_cvt_pk_bf16_f32 v170, v182, v183
	v_lshl_add_u64 v[166:167], v[166:167], 0, v[164:165]
	global_store_dwordx2 v[166:167], v[170:171], off
	v_cvt_pk_bf16_f32 v170, v174, v175
	v_cvt_pk_bf16_f32 v171, v168, v169
	global_store_dwordx2 v[166:167], v[170:171], off offset:32
	v_and_b32_e32 v166, 0x7e780, v139
	v_mov_b32_e32 v167, v113
	v_lshl_add_u64 v[166:167], s[46:47], 0, v[166:167]
	v_lshl_add_u64 v[182:183], v[166:167], 0, v[112:113]
	global_load_dwordx4 v[166:169], v[182:183], off offset:16
	s_nop 0
	global_load_dwordx4 v[182:185], v[182:183], off
	v_pk_mul_f32 v[186:187], v[136:137], v[56:57] op_sel_hi:[0,1]
	v_pk_mul_f32 v[174:175], v[136:137], v[60:61] op_sel_hi:[0,1]
	v_pk_mul_f32 v[176:177], v[136:137], v[58:59] op_sel_hi:[0,1]
	v_pk_mul_f32 v[170:171], v[136:137], v[62:63] op_sel_hi:[0,1]
	v_lshlrev_b32_e32 v139, 7, v152
	s_waitcnt vmcnt(0)
	v_mov_b32_e32 v188, v182
	v_mov_b32_e32 v189, v184
	v_mov_b32_e32 v184, v183
	v_pk_mul_f32 v[182:183], v[186:187], v[184:185]
	v_pk_mul_f32 v[186:187], v[186:187], v[188:189]
	v_pk_fma_f32 v[182:183], v[174:175], v[188:189], v[182:183] neg_lo:[0,0,1] neg_hi:[0,0,1]
	v_pk_fma_f32 v[174:175], v[174:175], v[184:185], v[186:187]
	v_mov_b32_e32 v185, v168
	v_mov_b32_e32 v168, v167
	v_mov_b32_e32 v184, v166
	v_pk_mul_f32 v[166:167], v[176:177], v[168:169]
	v_pk_mul_f32 v[176:177], v[176:177], v[184:185]
	v_pk_fma_f32 v[166:167], v[170:171], v[184:185], v[166:167] neg_lo:[0,0,1] neg_hi:[0,0,1]
	v_pk_fma_f32 v[168:169], v[170:171], v[168:169], v[176:177]
	v_cvt_pk_bf16_f32 v171, v166, v167
	v_lshlrev_b64 v[166:167], 6, v[154:155]
	v_lshl_add_u64 v[166:167], s[36:37], 0, v[166:167]
	v_cvt_pk_bf16_f32 v170, v182, v183
	v_lshl_add_u64 v[166:167], v[166:167], 0, v[164:165]
	global_store_dwordx2 v[166:167], v[170:171], off
	v_cvt_pk_bf16_f32 v170, v174, v175
	v_cvt_pk_bf16_f32 v171, v168, v169
	global_store_dwordx2 v[166:167], v[170:171], off offset:32
	v_and_b32_e32 v166, 0x7ef80, v139
	v_mov_b32_e32 v167, v113
	v_lshl_add_u64 v[166:167], s[46:47], 0, v[166:167]
	v_lshl_add_u64 v[182:183], v[166:167], 0, v[112:113]
	global_load_dwordx4 v[166:169], v[182:183], off offset:16
	s_nop 0
	global_load_dwordx4 v[182:185], v[182:183], off
	v_pk_mul_f32 v[186:187], v[134:135], v[40:41] op_sel_hi:[0,1]
	v_pk_mul_f32 v[174:175], v[134:135], v[44:45] op_sel_hi:[0,1]
	v_pk_mul_f32 v[176:177], v[134:135], v[42:43] op_sel_hi:[0,1]
	v_pk_mul_f32 v[170:171], v[134:135], v[46:47] op_sel_hi:[0,1]
	v_lshlrev_b32_e32 v139, 7, v150
	s_waitcnt vmcnt(0)
	v_mov_b32_e32 v188, v182
	v_mov_b32_e32 v189, v184
	v_mov_b32_e32 v184, v183
	v_pk_mul_f32 v[182:183], v[186:187], v[184:185]
	v_pk_mul_f32 v[186:187], v[186:187], v[188:189]
	v_pk_fma_f32 v[182:183], v[174:175], v[188:189], v[182:183] neg_lo:[0,0,1] neg_hi:[0,0,1]
	v_pk_fma_f32 v[174:175], v[174:175], v[184:185], v[186:187]
	v_mov_b32_e32 v185, v168
	v_mov_b32_e32 v168, v167
	v_mov_b32_e32 v184, v166
	v_pk_mul_f32 v[166:167], v[176:177], v[168:169]
	v_pk_mul_f32 v[176:177], v[176:177], v[184:185]
	v_pk_fma_f32 v[166:167], v[170:171], v[184:185], v[166:167] neg_lo:[0,0,1] neg_hi:[0,0,1]
	v_pk_fma_f32 v[168:169], v[170:171], v[168:169], v[176:177]
	v_cvt_pk_bf16_f32 v171, v166, v167
	v_lshlrev_b64 v[166:167], 6, v[152:153]
	v_lshl_add_u64 v[166:167], s[36:37], 0, v[166:167]
	v_cvt_pk_bf16_f32 v170, v182, v183
	v_lshl_add_u64 v[166:167], v[166:167], 0, v[164:165]
	global_store_dwordx2 v[166:167], v[170:171], off
	v_cvt_pk_bf16_f32 v170, v174, v175
	v_cvt_pk_bf16_f32 v171, v168, v169
	global_store_dwordx2 v[166:167], v[170:171], off offset:32
	v_and_b32_e32 v166, 0x7f780, v139
	v_mov_b32_e32 v167, v113
	v_lshl_add_u64 v[166:167], s[46:47], 0, v[166:167]
	v_lshl_add_u64 v[182:183], v[166:167], 0, v[112:113]
	global_load_dwordx4 v[166:169], v[182:183], off offset:16
	s_nop 0
	global_load_dwordx4 v[182:185], v[182:183], off
	v_pk_mul_f32 v[186:187], v[132:133], v[24:25] op_sel_hi:[0,1]
	v_pk_mul_f32 v[174:175], v[132:133], v[28:29] op_sel_hi:[0,1]
	v_pk_mul_f32 v[176:177], v[132:133], v[26:27] op_sel_hi:[0,1]
	v_pk_mul_f32 v[170:171], v[132:133], v[30:31] op_sel_hi:[0,1]
	v_lshlrev_b32_e32 v139, 7, v148
	s_waitcnt vmcnt(0)
	v_mov_b32_e32 v188, v182
	v_mov_b32_e32 v189, v184
	v_mov_b32_e32 v184, v183
	v_pk_mul_f32 v[182:183], v[186:187], v[184:185]
	v_pk_mul_f32 v[186:187], v[186:187], v[188:189]
	v_pk_fma_f32 v[182:183], v[174:175], v[188:189], v[182:183] neg_lo:[0,0,1] neg_hi:[0,0,1]
	v_pk_fma_f32 v[174:175], v[174:175], v[184:185], v[186:187]
	v_mov_b32_e32 v185, v168
	v_mov_b32_e32 v168, v167
	v_mov_b32_e32 v184, v166
	v_pk_mul_f32 v[166:167], v[176:177], v[168:169]
	v_pk_mul_f32 v[176:177], v[176:177], v[184:185]
	v_pk_fma_f32 v[166:167], v[170:171], v[184:185], v[166:167] neg_lo:[0,0,1] neg_hi:[0,0,1]
	v_pk_fma_f32 v[168:169], v[170:171], v[168:169], v[176:177]
	v_cvt_pk_bf16_f32 v171, v166, v167
	v_lshlrev_b64 v[166:167], 6, v[150:151]
	v_lshl_add_u64 v[166:167], s[36:37], 0, v[166:167]
	v_cvt_pk_bf16_f32 v170, v182, v183
	v_lshl_add_u64 v[166:167], v[166:167], 0, v[164:165]
	global_store_dwordx2 v[166:167], v[170:171], off
	v_cvt_pk_bf16_f32 v170, v174, v175
	v_cvt_pk_bf16_f32 v171, v168, v169
	global_store_dwordx2 v[166:167], v[170:171], off offset:32
	v_and_b32_e32 v166, 0x7ff80, v139
	v_mov_b32_e32 v167, v113
	v_lshl_add_u64 v[166:167], s[46:47], 0, v[166:167]
	v_lshl_add_u64 v[182:183], v[166:167], 0, v[112:113]
	global_load_dwordx4 v[166:169], v[182:183], off offset:16
	s_nop 0
	global_load_dwordx4 v[182:185], v[182:183], off
	v_pk_mul_f32 v[186:187], v[130:131], v[8:9] op_sel_hi:[0,1]
	v_pk_mul_f32 v[174:175], v[130:131], v[12:13] op_sel_hi:[0,1]
	v_pk_mul_f32 v[176:177], v[130:131], v[10:11] op_sel_hi:[0,1]
	v_pk_mul_f32 v[170:171], v[130:131], v[14:15] op_sel_hi:[0,1]
	s_waitcnt vmcnt(0)
	v_mov_b32_e32 v188, v182
	v_mov_b32_e32 v189, v184
	v_mov_b32_e32 v184, v183
	v_pk_mul_f32 v[182:183], v[186:187], v[184:185]
	v_pk_mul_f32 v[186:187], v[186:187], v[188:189]
	v_pk_fma_f32 v[182:183], v[174:175], v[188:189], v[182:183] neg_lo:[0,0,1] neg_hi:[0,0,1]
	v_pk_fma_f32 v[174:175], v[174:175], v[184:185], v[186:187]
	v_mov_b32_e32 v185, v168
	v_mov_b32_e32 v168, v167
	v_mov_b32_e32 v184, v166
	v_pk_mul_f32 v[166:167], v[176:177], v[168:169]
	v_pk_mul_f32 v[176:177], v[176:177], v[184:185]
	v_pk_fma_f32 v[166:167], v[170:171], v[184:185], v[166:167] neg_lo:[0,0,1] neg_hi:[0,0,1]
	v_pk_fma_f32 v[168:169], v[170:171], v[168:169], v[176:177]
	v_cvt_pk_bf16_f32 v171, v166, v167
	v_lshlrev_b64 v[166:167], 6, v[148:149]
	v_lshl_add_u64 v[166:167], s[36:37], 0, v[166:167]
	v_cvt_pk_bf16_f32 v170, v182, v183
	v_lshl_add_u64 v[164:165], v[166:167], 0, v[164:165]
	v_cvt_pk_bf16_f32 v166, v174, v175
	v_cvt_pk_bf16_f32 v167, v168, v169
	global_store_dwordx2 v[164:165], v[170:171], off
	global_store_dwordx2 v[164:165], v[166:167], off offset:32

.LBB0_542:
	s_add_i32 s9, s8, 0xfffe8000
	s_and_b32 s10, s8, 0x18000
	s_waitcnt vmcnt(8)
	s_barrier
	s_and_b32 s9, s9, 0x18000
	s_add_i32 s10, s7, s10
	v_add_u32_e32 v112, s9, v139
	v_or_b32_e32 v141, s9, v140
	s_add_i32 s18, s10, 0x400
	s_add_i32 s11, s10, 0x800
	s_add_i32 s9, s10, 0xc00
	s_add_i32 s8, s8, 0x8000
	s_cmp_eq_u32 s8, 0x100000
	ds_read_b128 v[162:165], v112
	ds_read_b128 v[142:145], v141
	ds_read_b128 v[146:149], v141 offset:1024
	ds_read_b128 v[150:153], v141 offset:2048
	ds_read_b128 v[158:161], v141 offset:3072
	ds_read_b128 v[166:169], v112 offset:1024
	ds_read_b128 v[174:177], v112 offset:2048
	ds_read_b128 v[182:185], v112 offset:3072
	s_waitcnt lgkmcnt(6)
	v_mfma_f32_16x16x32_bf16 v[126:129], v[142:145], v[162:165], v[126:129]
	s_waitcnt lgkmcnt(5)
	v_mfma_f32_16x16x32_bf16 v[122:125], v[146:149], v[162:165], v[122:125]
	s_waitcnt lgkmcnt(4)
	v_mfma_f32_16x16x32_bf16 v[118:121], v[150:153], v[162:165], v[118:121]
	s_waitcnt lgkmcnt(3)
	s_mov_b32 m0, s10
	v_mfma_f32_16x16x32_bf16 v[114:117], v[158:161], v[162:165], v[114:117]
	global_load_lds_dwordx4 v[136:137], off
	v_lshl_add_u64 v[136:137], v[136:137], 0, 64
	s_waitcnt lgkmcnt(2)
	v_mfma_f32_16x16x32_bf16 v[108:111], v[142:145], v[166:169], v[108:111]
	ds_read_b128 v[162:165], v112 offset:4096
	v_mfma_f32_16x16x32_bf16 v[104:107], v[146:149], v[166:169], v[104:107]
	v_mfma_f32_16x16x32_bf16 v[100:103], v[150:153], v[166:169], v[100:103]
	s_mov_b32 m0, s18
	v_mfma_f32_16x16x32_bf16 v[96:99], v[158:161], v[166:169], v[96:99]
	global_load_lds_dwordx4 v[134:135], off
	v_lshl_add_u64 v[134:135], v[134:135], 0, 64
	s_waitcnt lgkmcnt(2)
	v_mfma_f32_16x16x32_bf16 v[92:95], v[142:145], v[174:177], v[92:95]
	ds_read_b128 v[166:169], v112 offset:5120
	v_mfma_f32_16x16x32_bf16 v[88:91], v[146:149], v[174:177], v[88:91]
	v_mfma_f32_16x16x32_bf16 v[84:87], v[150:153], v[174:177], v[84:87]
	s_mov_b32 m0, s11
	v_mfma_f32_16x16x32_bf16 v[80:83], v[158:161], v[174:177], v[80:83]
	global_load_lds_dwordx4 v[132:133], off
	v_lshl_add_u64 v[132:133], v[132:133], 0, 64
	s_waitcnt lgkmcnt(2)
	v_mfma_f32_16x16x32_bf16 v[76:79], v[142:145], v[182:185], v[76:79]
	ds_read_b128 v[174:177], v112 offset:6144
	v_mfma_f32_16x16x32_bf16 v[72:75], v[146:149], v[182:185], v[72:75]
	v_mfma_f32_16x16x32_bf16 v[68:71], v[150:153], v[182:185], v[68:71]
	s_mov_b32 m0, s9
	v_mfma_f32_16x16x32_bf16 v[64:67], v[158:161], v[182:185], v[64:67]
	global_load_lds_dwordx4 v[130:131], off
	v_lshl_add_u64 v[130:131], v[130:131], 0, 64
	s_waitcnt lgkmcnt(2)
	v_mfma_f32_16x16x32_bf16 v[60:63], v[142:145], v[162:165], v[60:63]
	ds_read_b128 v[182:185], v112 offset:7168
	v_mfma_f32_16x16x32_bf16 v[56:59], v[146:149], v[162:165], v[56:59]
	v_mfma_f32_16x16x32_bf16 v[52:55], v[150:153], v[162:165], v[52:55]
	v_mfma_f32_16x16x32_bf16 v[48:51], v[158:161], v[162:165], v[48:51]
	s_waitcnt lgkmcnt(2)
	v_mfma_f32_16x16x32_bf16 v[44:47], v[142:145], v[166:169], v[44:47]
	v_mfma_f32_16x16x32_bf16 v[40:43], v[146:149], v[166:169], v[40:43]
	v_mfma_f32_16x16x32_bf16 v[36:39], v[150:153], v[166:169], v[36:39]
	v_mfma_f32_16x16x32_bf16 v[32:35], v[158:161], v[166:169], v[32:35]
	s_waitcnt lgkmcnt(1)
	v_mfma_f32_16x16x32_bf16 v[28:31], v[142:145], v[174:177], v[28:31]
	v_mfma_f32_16x16x32_bf16 v[24:27], v[146:149], v[174:177], v[24:27]
	v_mfma_f32_16x16x32_bf16 v[20:23], v[150:153], v[174:177], v[20:23]
	v_mfma_f32_16x16x32_bf16 v[16:19], v[158:161], v[174:177], v[16:19]
	s_waitcnt lgkmcnt(0)
	v_mfma_f32_16x16x32_bf16 v[12:15], v[142:145], v[182:185], v[12:15]
	v_mfma_f32_16x16x32_bf16 v[8:11], v[146:149], v[182:185], v[8:11]
	v_mfma_f32_16x16x32_bf16 v[4:7], v[150:153], v[182:185], v[4:7]
	v_mfma_f32_16x16x32_bf16 v[0:3], v[158:161], v[182:185], v[0:3]
	s_cbranch_scc0 .LBB0_542
	s_waitcnt vmcnt(8)
	s_barrier
	v_add_u32_e32 v112, 0x8000, v139
	v_or_b32_e32 v141, 0x8000, v140
	ds_read_b128 v[130:133], v141
	ds_read_b128 v[134:137], v141 offset:1024
	ds_read_b128 v[142:145], v141 offset:2048
	ds_read_b128 v[146:149], v141 offset:3072
	ds_read_b128 v[150:153], v112
	ds_read_b128 v[158:161], v112 offset:1024
	ds_read_b128 v[162:165], v112 offset:2048
	ds_read_b128 v[166:169], v112 offset:3072
	v_add_u32_e32 v141, 0x10000, v139
	s_waitcnt lgkmcnt(0)
	v_or_b32_e32 v154, 0x10000, v140
	v_mfma_f32_16x16x32_bf16 v[126:129], v[130:133], v[150:153], v[126:129]
	v_add_u32_e32 v139, 0x18000, v139
	s_lshl_b32 s8, s6, 8
	v_and_b32_e32 v170, 15, v138
	v_mfma_f32_16x16x32_bf16 v[122:125], v[134:137], v[150:153], v[122:125]
	s_and_b32 s18, s8, 0xffffc000
	s_ashr_i32 s7, s6, 1
	s_and_b32 s7, s7, 0xffffff80
	v_mfma_f32_16x16x32_bf16 v[118:121], v[142:145], v[150:153], v[118:121]
	s_and_b32 s6, s6, 0xc0
	s_add_i32 s8, s4, s7
	s_or_b32 s4, s5, s6
	v_mfma_f32_16x16x32_bf16 v[114:117], v[146:149], v[150:153], v[114:117]
	s_ashr_i32 s10, s4, 6
	s_ashr_i32 s11, s10, 31
	v_mfma_f32_16x16x32_bf16 v[108:111], v[130:133], v[158:161], v[108:111]
	v_mfma_f32_16x16x32_bf16 v[104:107], v[134:137], v[158:161], v[104:107]
	v_mfma_f32_16x16x32_bf16 v[100:103], v[142:145], v[158:161], v[100:103]
	v_mfma_f32_16x16x32_bf16 v[96:99], v[146:149], v[158:161], v[96:99]
	v_mfma_f32_16x16x32_bf16 v[92:95], v[130:133], v[162:165], v[92:95]
	v_mfma_f32_16x16x32_bf16 v[88:91], v[134:137], v[162:165], v[88:91]
	v_mfma_f32_16x16x32_bf16 v[84:87], v[142:145], v[162:165], v[84:87]
	v_mfma_f32_16x16x32_bf16 v[80:83], v[146:149], v[162:165], v[80:83]
	v_mfma_f32_16x16x32_bf16 v[76:79], v[130:133], v[166:169], v[76:79]
	v_mfma_f32_16x16x32_bf16 v[72:75], v[134:137], v[166:169], v[72:75]
	v_mfma_f32_16x16x32_bf16 v[68:71], v[142:145], v[166:169], v[68:71]
	v_mfma_f32_16x16x32_bf16 v[64:67], v[146:149], v[166:169], v[64:67]
	ds_read_b128 v[150:153], v112 offset:4096
	ds_read_b128 v[158:161], v112 offset:5120
	ds_read_b128 v[162:165], v112 offset:6144
	ds_read_b128 v[166:169], v112 offset:7168
	s_waitcnt lgkmcnt(0)
	s_waitcnt vmcnt(4)
	s_barrier
	v_mfma_f32_16x16x32_bf16 v[60:63], v[130:133], v[150:153], v[60:63]
	v_and_b32_e32 v112, 63, v138
	v_mfma_f32_16x16x32_bf16 v[56:59], v[134:137], v[150:153], v[56:59]
	v_mfma_f32_16x16x32_bf16 v[52:55], v[142:145], v[150:153], v[52:55]
	v_mfma_f32_16x16x32_bf16 v[48:51], v[146:149], v[150:153], v[48:51]
	v_mfma_f32_16x16x32_bf16 v[44:47], v[130:133], v[158:161], v[44:47]
	v_mfma_f32_16x16x32_bf16 v[40:43], v[134:137], v[158:161], v[40:43]
	v_mfma_f32_16x16x32_bf16 v[36:39], v[142:145], v[158:161], v[36:39]
	v_mfma_f32_16x16x32_bf16 v[32:35], v[146:149], v[158:161], v[32:35]
	v_mfma_f32_16x16x32_bf16 v[28:31], v[130:133], v[162:165], v[28:31]
	v_mfma_f32_16x16x32_bf16 v[24:27], v[134:137], v[162:165], v[24:27]
	v_mfma_f32_16x16x32_bf16 v[20:23], v[142:145], v[162:165], v[20:23]
	v_mfma_f32_16x16x32_bf16 v[16:19], v[146:149], v[162:165], v[16:19]
	v_mfma_f32_16x16x32_bf16 v[12:15], v[130:133], v[166:169], v[12:15]
	v_mfma_f32_16x16x32_bf16 v[8:11], v[134:137], v[166:169], v[8:11]
	v_mfma_f32_16x16x32_bf16 v[4:7], v[142:145], v[166:169], v[4:7]
	v_mfma_f32_16x16x32_bf16 v[0:3], v[146:149], v[166:169], v[0:3]
	ds_read_b128 v[130:133], v154
	ds_read_b128 v[134:137], v154 offset:1024
	ds_read_b128 v[142:145], v154 offset:2048
	ds_read_b128 v[146:149], v154 offset:3072
	ds_read_b128 v[150:153], v141
	ds_read_b128 v[158:161], v141 offset:1024
	ds_read_b128 v[162:165], v141 offset:2048
	ds_read_b128 v[166:169], v141 offset:3072
	s_nop 0
	s_waitcnt lgkmcnt(0)
	s_nop 0
	v_mfma_f32_16x16x32_bf16 v[126:129], v[130:133], v[150:153], v[126:129]
	v_mfma_f32_16x16x32_bf16 v[122:125], v[134:137], v[150:153], v[122:125]
	v_mfma_f32_16x16x32_bf16 v[118:121], v[142:145], v[150:153], v[118:121]
	v_mfma_f32_16x16x32_bf16 v[114:117], v[146:149], v[150:153], v[114:117]
	v_mfma_f32_16x16x32_bf16 v[108:111], v[130:133], v[158:161], v[108:111]
	v_mfma_f32_16x16x32_bf16 v[104:107], v[134:137], v[158:161], v[104:107]
	v_mfma_f32_16x16x32_bf16 v[100:103], v[142:145], v[158:161], v[100:103]
	v_mfma_f32_16x16x32_bf16 v[150:153], v[146:149], v[158:161], v[96:99]
	v_mfma_f32_16x16x32_bf16 v[92:95], v[130:133], v[162:165], v[92:95]
	v_mfma_f32_16x16x32_bf16 v[88:91], v[134:137], v[162:165], v[88:91]
	v_mfma_f32_16x16x32_bf16 v[84:87], v[142:145], v[162:165], v[84:87]
	v_mfma_f32_16x16x32_bf16 v[80:83], v[146:149], v[162:165], v[80:83]
	v_mfma_f32_16x16x32_bf16 v[76:79], v[130:133], v[166:169], v[76:79]
	v_mfma_f32_16x16x32_bf16 v[72:75], v[134:137], v[166:169], v[72:75]
	v_mfma_f32_16x16x32_bf16 v[68:71], v[142:145], v[166:169], v[68:71]
	v_mfma_f32_16x16x32_bf16 v[64:67], v[146:149], v[166:169], v[64:67]
	ds_read_b128 v[96:99], v141 offset:4096
	ds_read_b128 v[158:161], v141 offset:5120
	ds_read_b128 v[162:165], v141 offset:6144
	ds_read_b128 v[166:169], v141 offset:7168
	s_waitcnt lgkmcnt(0)
	s_waitcnt vmcnt(0)
	s_barrier
	v_mfma_f32_16x16x32_bf16 v[60:63], v[130:133], v[96:99], v[60:63]
	v_mfma_f32_16x16x32_bf16 v[56:59], v[134:137], v[96:99], v[56:59]
	v_mfma_f32_16x16x32_bf16 v[52:55], v[142:145], v[96:99], v[52:55]
	v_mfma_f32_16x16x32_bf16 v[48:51], v[146:149], v[96:99], v[48:51]
	v_mfma_f32_16x16x32_bf16 v[44:47], v[130:133], v[158:161], v[44:47]
	v_mfma_f32_16x16x32_bf16 v[40:43], v[134:137], v[158:161], v[40:43]
	v_mfma_f32_16x16x32_bf16 v[36:39], v[142:145], v[158:161], v[36:39]
	v_mfma_f32_16x16x32_bf16 v[32:35], v[146:149], v[158:161], v[32:35]
	v_mfma_f32_16x16x32_bf16 v[28:31], v[130:133], v[162:165], v[28:31]
	v_mfma_f32_16x16x32_bf16 v[24:27], v[134:137], v[162:165], v[24:27]
	v_mfma_f32_16x16x32_bf16 v[20:23], v[142:145], v[162:165], v[20:23]
	v_mfma_f32_16x16x32_bf16 v[16:19], v[146:149], v[162:165], v[16:19]
	v_mfma_f32_16x16x32_bf16 v[12:15], v[130:133], v[166:169], v[12:15]
	v_mfma_f32_16x16x32_bf16 v[8:11], v[134:137], v[166:169], v[8:11]
	v_mfma_f32_16x16x32_bf16 v[4:7], v[142:145], v[166:169], v[4:7]
	v_mfma_f32_16x16x32_bf16 v[0:3], v[146:149], v[166:169], v[0:3]
	v_or_b32_e32 v148, 0x18000, v140
	ds_read_b128 v[130:133], v148
	ds_read_b128 v[134:137], v148 offset:1024
	ds_read_b128 v[140:143], v148 offset:2048
	ds_read_b128 v[144:147], v148 offset:3072
	ds_read_b128 v[96:99], v139
	ds_read_b128 v[158:161], v139 offset:1024
	ds_read_b128 v[162:165], v139 offset:2048
	ds_read_b128 v[166:169], v139 offset:3072
	s_nop 0
	s_waitcnt lgkmcnt(0)
	s_nop 0
	v_mfma_f32_16x16x32_bf16 v[126:129], v[130:133], v[96:99], v[126:129]
	v_mfma_f32_16x16x32_bf16 v[174:177], v[134:137], v[96:99], v[122:125]
	v_mfma_f32_16x16x32_bf16 v[182:185], v[140:143], v[96:99], v[118:121]
	v_mfma_f32_16x16x32_bf16 v[114:117], v[144:147], v[96:99], v[114:117]
	v_mfma_f32_16x16x32_bf16 v[96:99], v[140:143], v[158:161], v[100:103]
	v_mfma_f32_16x16x32_bf16 v[100:103], v[144:147], v[158:161], v[150:153]
	ds_read_b128 v[118:121], v139 offset:4096
	ds_read_b128 v[122:125], v139 offset:5120
	ds_read_b128 v[148:151], v139 offset:6144
	ds_read_b128 v[152:155], v139 offset:7168
	s_waitcnt lgkmcnt(0)
	s_barrier
	v_mfma_f32_16x16x32_bf16 v[60:63], v[130:133], v[118:121], v[60:63]
	v_mfma_f32_16x16x32_bf16 v[56:59], v[134:137], v[118:121], v[56:59]
	v_mfma_f32_16x16x32_bf16 v[52:55], v[140:143], v[118:121], v[52:55]
	v_mfma_f32_16x16x32_bf16 v[48:51], v[144:147], v[118:121], v[48:51]
	v_bfe_u32 v119, v138, 5, 1
	v_lshrrev_b32_e32 v121, 1, v138
	v_lshlrev_b32_e32 v118, 7, v170
	v_mfma_f32_16x16x32_bf16 v[44:47], v[130:133], v[122:125], v[44:47]
	v_and_b32_e32 v121, 8, v121
	v_and_b32_e32 v120, 7, v138
	v_mfma_f32_16x16x32_bf16 v[40:43], v[134:137], v[122:125], v[40:43]
	v_mfma_f32_16x16x32_bf16 v[36:39], v[140:143], v[122:125], v[36:39]
	v_mfma_f32_16x16x32_bf16 v[32:35], v[144:147], v[122:125], v[32:35]
	v_mul_f32_e32 v125, v127, v127
	v_bitop3_b32 v124, v119, v138, 7 bitop3:0x78
	v_or3_b32 v123, s18, v118, v121
	v_fmac_f32_e32 v125, v126, v126
	v_lshlrev_b32_e32 v124, 4, v124
	v_fmac_f32_e32 v125, v128, v128
	v_cvt_pk_bf16_f32 v126, v126, v127
	v_cvt_pk_bf16_f32 v127, v128, v129
	v_or_b32_e32 v128, v123, v124
	s_waitcnt vmcnt(0)
	ds_write_b64 v128, v[126:127]
	v_mul_f32_e32 v126, v175, v175
	v_fmac_f32_e32 v126, v174, v174
	v_fmac_f32_e32 v126, v176, v176
	v_fmac_f32_e32 v125, v129, v129
	v_fmac_f32_e32 v126, v177, v177
	v_add_f32_e32 v125, v125, v126
	v_bitop3_b32 v126, v119, v120, 2 bitop3:0x36
	v_lshlrev_b32_e32 v126, 4, v126
	v_cvt_pk_bf16_f32 v128, v174, v175
	v_cvt_pk_bf16_f32 v129, v176, v177
	v_or_b32_e32 v127, v123, v126
	ds_write_b64 v127, v[128:129]
	v_mul_f32_e32 v127, v183, v183
	v_fmac_f32_e32 v127, v182, v182
	v_fmac_f32_e32 v127, v184, v184
	v_fmac_f32_e32 v127, v185, v185
	v_add_f32_e32 v127, v125, v127
	v_bitop3_b32 v125, v119, v120, 4 bitop3:0x36
	v_lshlrev_b32_e32 v125, 4, v125
	v_mfma_f32_16x16x32_bf16 v[108:111], v[130:133], v[158:161], v[108:111]
	v_cvt_pk_bf16_f32 v128, v182, v183
	v_cvt_pk_bf16_f32 v129, v184, v185
	v_and_b32_e32 v121, 64, v172
	v_mfma_f32_16x16x32_bf16 v[92:95], v[130:133], v[162:165], v[92:95]
	v_xor_b32_e32 v118, 16, v172
	v_add_u32_e32 v122, 64, v121
	v_cmp_lt_i32_e32 vcc, v118, v122
	v_mfma_f32_16x16x32_bf16 v[76:79], v[130:133], v[166:169], v[76:79]
	s_nop 0
	v_cndmask_b32_e32 v118, v172, v118, vcc
	v_lshlrev_b32_e32 v121, 2, v118
	v_mfma_f32_16x16x32_bf16 v[28:31], v[130:133], v[148:151], v[28:31]
	v_xor_b32_e32 v118, 32, v172
	v_cmp_lt_i32_e32 vcc, v118, v122
	v_mfma_f32_16x16x32_bf16 v[12:15], v[130:133], v[152:155], v[12:15]
	v_or_b32_e32 v130, v123, v125
	ds_write_b64 v130, v[128:129]
	v_mul_f32_e32 v128, v115, v115
	v_fmac_f32_e32 v128, v114, v114
	v_fmac_f32_e32 v128, v116, v116
	v_fmac_f32_e32 v128, v117, v117
	v_add_f32_e32 v127, v127, v128
	v_cvt_pk_bf16_f32 v128, v114, v115
	v_bitop3_b32 v114, v119, v120, 6 bitop3:0x36
	v_lshlrev_b32_e32 v114, 4, v114
	v_cvt_pk_bf16_f32 v129, v116, v117
	v_or_b32_e32 v115, v123, v114
	ds_write_b64 v115, v[128:129]
	ds_bpermute_b32 v115, v121, v127
	v_cndmask_b32_e32 v118, v172, v118, vcc
	v_lshlrev_b32_e32 v122, 2, v118
	v_mfma_f32_16x16x32_bf16 v[104:107], v[134:137], v[158:161], v[104:107]
	v_cmp_gt_u32_e32 vcc, 16, v112
	s_waitcnt lgkmcnt(0)
	v_add_f32_e32 v115, v127, v115
	ds_bpermute_b32 v116, v122, v115
	v_mfma_f32_16x16x32_bf16 v[88:91], v[134:137], v[162:165], v[88:91]
	v_or_b32_e32 v118, s8, v170
	v_mfma_f32_16x16x32_bf16 v[84:87], v[140:143], v[162:165], v[84:87]
	v_mfma_f32_16x16x32_bf16 v[80:83], v[144:147], v[162:165], v[80:83]
	v_mfma_f32_16x16x32_bf16 v[72:75], v[134:137], v[166:169], v[72:75]
	v_mfma_f32_16x16x32_bf16 v[68:71], v[140:143], v[166:169], v[68:71]
	v_mfma_f32_16x16x32_bf16 v[64:67], v[144:147], v[166:169], v[64:67]
	v_mfma_f32_16x16x32_bf16 v[24:27], v[134:137], v[148:151], v[24:27]
	v_mfma_f32_16x16x32_bf16 v[20:23], v[140:143], v[148:151], v[20:23]
	v_mfma_f32_16x16x32_bf16 v[16:19], v[144:147], v[148:151], v[16:19]
	v_mfma_f32_16x16x32_bf16 v[8:11], v[134:137], v[152:155], v[8:11]
	v_mfma_f32_16x16x32_bf16 v[4:7], v[140:143], v[152:155], v[4:7]
	v_mfma_f32_16x16x32_bf16 v[0:3], v[144:147], v[152:155], v[0:3]
	s_and_saveexec_b64 s[6:7], vcc
	s_cbranch_execz .LBB0_545
	v_ashrrev_i32_e32 v119, 31, v118
	s_waitcnt lgkmcnt(0)
	v_add_f32_e32 v115, v115, v116
	v_lshlrev_b64 v[116:117], 6, v[118:119]
	v_lshl_add_u64 v[116:117], s[44:45], 0, v[116:117]
	v_lshl_add_u64 v[116:117], s[10:11], 2, v[116:117]
	global_store_dword v[116:117], v115, off

.LBB0_806:
	s_add_i32 s8, s5, 0xfffe8000
	s_and_b32 s9, s5, 0x18000
	s_waitcnt vmcnt(8)
	s_barrier
	s_and_b32 s8, s8, 0x18000
	s_add_i32 s9, s4, s9
	v_add_u32_e32 v128, s8, v160
	v_or_b32_e32 v170, s8, v161
	s_add_i32 s11, s9, 0x400
	s_add_i32 s10, s9, 0x800
	s_add_i32 s8, s9, 0xc00
	s_add_i32 s5, s5, 0x8000
	s_cmp_eq_u32 s5, 0x100000
	ds_read_b128 v[182:185], v128
	ds_read_b128 v[162:165], v170
	ds_read_b128 v[166:169], v170 offset:1024
	ds_read_b128 v[174:177], v170 offset:2048
	ds_read_b128 v[178:181], v170 offset:3072
	ds_read_b128 v[186:189], v128 offset:1024
	ds_read_b128 v[190:193], v128 offset:2048
	ds_read_b128 v[194:197], v128 offset:3072
	s_waitcnt lgkmcnt(6)
	v_mfma_f32_16x16x32_bf16 v[124:127], v[162:165], v[182:185], v[124:127]
	s_waitcnt lgkmcnt(5)
	v_mfma_f32_16x16x32_bf16 v[120:123], v[166:169], v[182:185], v[120:123]
	s_waitcnt lgkmcnt(4)
	v_mfma_f32_16x16x32_bf16 v[116:119], v[174:177], v[182:185], v[116:119]
	s_waitcnt lgkmcnt(3)
	s_mov_b32 m0, s9
	v_mfma_f32_16x16x32_bf16 v[112:115], v[178:181], v[182:185], v[112:115]
	global_load_lds_dwordx4 v[136:137], off
	v_lshl_add_u64 v[136:137], v[136:137], 0, 64
	s_waitcnt lgkmcnt(2)
	v_mfma_f32_16x16x32_bf16 v[108:111], v[162:165], v[186:189], v[108:111]
	ds_read_b128 v[182:185], v128 offset:4096
	v_mfma_f32_16x16x32_bf16 v[104:107], v[166:169], v[186:189], v[104:107]
	v_mfma_f32_16x16x32_bf16 v[100:103], v[174:177], v[186:189], v[100:103]
	s_mov_b32 m0, s11
	v_mfma_f32_16x16x32_bf16 v[96:99], v[178:181], v[186:189], v[96:99]
	global_load_lds_dwordx4 v[134:135], off
	v_lshl_add_u64 v[134:135], v[134:135], 0, 64
	s_waitcnt lgkmcnt(2)
	v_mfma_f32_16x16x32_bf16 v[92:95], v[162:165], v[190:193], v[92:95]
	ds_read_b128 v[186:189], v128 offset:5120
	v_mfma_f32_16x16x32_bf16 v[88:91], v[166:169], v[190:193], v[88:91]
	v_mfma_f32_16x16x32_bf16 v[84:87], v[174:177], v[190:193], v[84:87]
	s_mov_b32 m0, s10
	v_mfma_f32_16x16x32_bf16 v[80:83], v[178:181], v[190:193], v[80:83]
	global_load_lds_dwordx4 v[132:133], off
	v_lshl_add_u64 v[132:133], v[132:133], 0, 64
	s_waitcnt lgkmcnt(2)
	v_mfma_f32_16x16x32_bf16 v[76:79], v[162:165], v[194:197], v[76:79]
	ds_read_b128 v[190:193], v128 offset:6144
	v_mfma_f32_16x16x32_bf16 v[72:75], v[166:169], v[194:197], v[72:75]
	v_mfma_f32_16x16x32_bf16 v[68:71], v[174:177], v[194:197], v[68:71]
	s_mov_b32 m0, s8
	v_mfma_f32_16x16x32_bf16 v[64:67], v[178:181], v[194:197], v[64:67]
	global_load_lds_dwordx4 v[130:131], off
	v_lshl_add_u64 v[130:131], v[130:131], 0, 64
	s_waitcnt lgkmcnt(2)
	v_mfma_f32_16x16x32_bf16 v[60:63], v[162:165], v[182:185], v[60:63]
	ds_read_b128 v[194:197], v128 offset:7168
	v_mfma_f32_16x16x32_bf16 v[56:59], v[166:169], v[182:185], v[56:59]
	v_mfma_f32_16x16x32_bf16 v[52:55], v[174:177], v[182:185], v[52:55]
	v_mfma_f32_16x16x32_bf16 v[48:51], v[178:181], v[182:185], v[48:51]
	s_waitcnt lgkmcnt(2)
	v_mfma_f32_16x16x32_bf16 v[44:47], v[162:165], v[186:189], v[44:47]
	v_mfma_f32_16x16x32_bf16 v[40:43], v[166:169], v[186:189], v[40:43]
	v_mfma_f32_16x16x32_bf16 v[36:39], v[174:177], v[186:189], v[36:39]
	v_mfma_f32_16x16x32_bf16 v[32:35], v[178:181], v[186:189], v[32:35]
	s_waitcnt lgkmcnt(1)
	v_mfma_f32_16x16x32_bf16 v[28:31], v[162:165], v[190:193], v[28:31]
	v_mfma_f32_16x16x32_bf16 v[24:27], v[166:169], v[190:193], v[24:27]
	v_mfma_f32_16x16x32_bf16 v[20:23], v[174:177], v[190:193], v[20:23]
	v_mfma_f32_16x16x32_bf16 v[16:19], v[178:181], v[190:193], v[16:19]
	s_waitcnt lgkmcnt(0)
	v_mfma_f32_16x16x32_bf16 v[12:15], v[162:165], v[194:197], v[12:15]
	v_mfma_f32_16x16x32_bf16 v[8:11], v[166:169], v[194:197], v[8:11]
	v_mfma_f32_16x16x32_bf16 v[4:7], v[174:177], v[194:197], v[4:7]
	v_mfma_f32_16x16x32_bf16 v[0:3], v[178:181], v[194:197], v[0:3]
	s_cbranch_scc0 .LBB0_806
	s_waitcnt vmcnt(8)
	s_barrier
	v_add_u32_e32 v128, 0x8000, v160
	v_or_b32_e32 v170, 0x8000, v161
	ds_read_b128 v[130:133], v170
	ds_read_b128 v[134:137], v170 offset:1024
	ds_read_b128 v[162:165], v170 offset:2048
	ds_read_b128 v[166:169], v170 offset:3072
	ds_read_b128 v[174:177], v128
	ds_read_b128 v[178:181], v128 offset:1024
	ds_read_b128 v[182:185], v128 offset:2048
	ds_read_b128 v[186:189], v128 offset:3072
	v_or_b32_e32 v170, 0x10000, v161
	s_waitcnt lgkmcnt(0)
	v_or_b32_e32 v173, 0x18000, v161
	v_mfma_f32_16x16x32_bf16 v[124:127], v[130:133], v[174:177], v[124:127]
	s_cmp_eq_u32 s13, 2
	s_cselect_b64 s[8:9], -1, 0
	s_cmp_eq_u32 s13, 3
	v_mfma_f32_16x16x32_bf16 v[120:123], v[134:137], v[174:177], v[120:123]
	s_cselect_b64 s[4:5], -1, 0
	s_and_b64 vcc, exec, s[4:5]
	v_mfma_f32_16x16x32_bf16 v[116:119], v[162:165], v[174:177], v[116:119]
	v_mfma_f32_16x16x32_bf16 v[112:115], v[166:169], v[174:177], v[112:115]
	v_mfma_f32_16x16x32_bf16 v[108:111], v[130:133], v[178:181], v[108:111]
	v_mfma_f32_16x16x32_bf16 v[104:107], v[134:137], v[178:181], v[104:107]
	v_mfma_f32_16x16x32_bf16 v[100:103], v[162:165], v[178:181], v[100:103]
	v_mfma_f32_16x16x32_bf16 v[96:99], v[166:169], v[178:181], v[96:99]
	v_mfma_f32_16x16x32_bf16 v[92:95], v[130:133], v[182:185], v[92:95]
	v_mfma_f32_16x16x32_bf16 v[88:91], v[134:137], v[182:185], v[88:91]
	v_mfma_f32_16x16x32_bf16 v[84:87], v[162:165], v[182:185], v[84:87]
	v_mfma_f32_16x16x32_bf16 v[80:83], v[166:169], v[182:185], v[80:83]
	v_mfma_f32_16x16x32_bf16 v[76:79], v[130:133], v[186:189], v[76:79]
	v_mfma_f32_16x16x32_bf16 v[72:75], v[134:137], v[186:189], v[72:75]
	v_mfma_f32_16x16x32_bf16 v[68:71], v[162:165], v[186:189], v[68:71]
	v_mfma_f32_16x16x32_bf16 v[64:67], v[166:169], v[186:189], v[64:67]
	ds_read_b128 v[174:177], v128 offset:4096
	ds_read_b128 v[178:181], v128 offset:5120
	ds_read_b128 v[182:185], v128 offset:6144
	ds_read_b128 v[186:189], v128 offset:7168
	s_waitcnt lgkmcnt(0)
	s_waitcnt vmcnt(4)
	s_barrier
	v_mfma_f32_16x16x32_bf16 v[60:63], v[130:133], v[174:177], v[60:63]
	v_add_u32_e32 v128, 0x10000, v160
	v_mfma_f32_16x16x32_bf16 v[56:59], v[134:137], v[174:177], v[56:59]
	v_mfma_f32_16x16x32_bf16 v[52:55], v[162:165], v[174:177], v[52:55]
	v_mfma_f32_16x16x32_bf16 v[48:51], v[166:169], v[174:177], v[48:51]
	v_mfma_f32_16x16x32_bf16 v[44:47], v[130:133], v[178:181], v[44:47]
	v_mfma_f32_16x16x32_bf16 v[40:43], v[134:137], v[178:181], v[40:43]
	v_mfma_f32_16x16x32_bf16 v[36:39], v[162:165], v[178:181], v[36:39]
	v_mfma_f32_16x16x32_bf16 v[32:35], v[166:169], v[178:181], v[32:35]
	v_mfma_f32_16x16x32_bf16 v[28:31], v[130:133], v[182:185], v[28:31]
	v_mfma_f32_16x16x32_bf16 v[24:27], v[134:137], v[182:185], v[24:27]
	v_mfma_f32_16x16x32_bf16 v[20:23], v[162:165], v[182:185], v[20:23]
	v_mfma_f32_16x16x32_bf16 v[16:19], v[166:169], v[182:185], v[16:19]
	v_mfma_f32_16x16x32_bf16 v[12:15], v[130:133], v[186:189], v[12:15]
	v_mfma_f32_16x16x32_bf16 v[8:11], v[134:137], v[186:189], v[8:11]
	v_mfma_f32_16x16x32_bf16 v[4:7], v[162:165], v[186:189], v[4:7]
	v_mfma_f32_16x16x32_bf16 v[0:3], v[166:169], v[186:189], v[0:3]
	ds_read_b128 v[130:133], v170
	ds_read_b128 v[134:137], v170 offset:1024
	ds_read_b128 v[162:165], v170 offset:2048
	ds_read_b128 v[166:169], v170 offset:3072
	ds_read_b128 v[174:177], v128
	ds_read_b128 v[178:181], v128 offset:1024
	ds_read_b128 v[182:185], v128 offset:2048
	ds_read_b128 v[186:189], v128 offset:3072
	s_nop 0
	s_waitcnt lgkmcnt(0)
	s_nop 0
	v_mfma_f32_16x16x32_bf16 v[124:127], v[130:133], v[174:177], v[124:127]
	v_mfma_f32_16x16x32_bf16 v[120:123], v[134:137], v[174:177], v[120:123]
	v_mfma_f32_16x16x32_bf16 v[116:119], v[162:165], v[174:177], v[116:119]
	v_mfma_f32_16x16x32_bf16 v[112:115], v[166:169], v[174:177], v[112:115]
	v_mfma_f32_16x16x32_bf16 v[108:111], v[130:133], v[178:181], v[108:111]
	v_mfma_f32_16x16x32_bf16 v[104:107], v[134:137], v[178:181], v[104:107]
	v_mfma_f32_16x16x32_bf16 v[100:103], v[162:165], v[178:181], v[100:103]
	v_mfma_f32_16x16x32_bf16 v[96:99], v[166:169], v[178:181], v[96:99]
	v_mfma_f32_16x16x32_bf16 v[92:95], v[130:133], v[182:185], v[92:95]
	v_mfma_f32_16x16x32_bf16 v[88:91], v[134:137], v[182:185], v[88:91]
	v_mfma_f32_16x16x32_bf16 v[84:87], v[162:165], v[182:185], v[84:87]
	v_mfma_f32_16x16x32_bf16 v[80:83], v[166:169], v[182:185], v[80:83]
	v_mfma_f32_16x16x32_bf16 v[76:79], v[130:133], v[186:189], v[76:79]
	v_mfma_f32_16x16x32_bf16 v[72:75], v[134:137], v[186:189], v[72:75]
	v_mfma_f32_16x16x32_bf16 v[68:71], v[162:165], v[186:189], v[68:71]
	v_mfma_f32_16x16x32_bf16 v[64:67], v[166:169], v[186:189], v[64:67]
	ds_read_b128 v[174:177], v128 offset:4096
	ds_read_b128 v[178:181], v128 offset:5120
	ds_read_b128 v[182:185], v128 offset:6144
	ds_read_b128 v[186:189], v128 offset:7168
	s_waitcnt lgkmcnt(0)
	s_waitcnt vmcnt(0)
	s_barrier
	v_mfma_f32_16x16x32_bf16 v[60:63], v[130:133], v[174:177], v[60:63]
	v_add_u32_e32 v128, 0x18000, v160
	v_mfma_f32_16x16x32_bf16 v[56:59], v[134:137], v[174:177], v[56:59]
	v_mfma_f32_16x16x32_bf16 v[52:55], v[162:165], v[174:177], v[52:55]
	v_mfma_f32_16x16x32_bf16 v[48:51], v[166:169], v[174:177], v[48:51]
	v_mfma_f32_16x16x32_bf16 v[44:47], v[130:133], v[178:181], v[44:47]
	v_mfma_f32_16x16x32_bf16 v[40:43], v[134:137], v[178:181], v[40:43]
	v_mfma_f32_16x16x32_bf16 v[36:39], v[162:165], v[178:181], v[36:39]
	v_mfma_f32_16x16x32_bf16 v[32:35], v[166:169], v[178:181], v[32:35]
	v_mfma_f32_16x16x32_bf16 v[28:31], v[130:133], v[182:185], v[28:31]
	v_mfma_f32_16x16x32_bf16 v[24:27], v[134:137], v[182:185], v[24:27]
	v_mfma_f32_16x16x32_bf16 v[20:23], v[162:165], v[182:185], v[20:23]
	v_mfma_f32_16x16x32_bf16 v[16:19], v[166:169], v[182:185], v[16:19]
	v_mfma_f32_16x16x32_bf16 v[12:15], v[130:133], v[186:189], v[12:15]
	v_mfma_f32_16x16x32_bf16 v[8:11], v[134:137], v[186:189], v[8:11]
	v_mfma_f32_16x16x32_bf16 v[4:7], v[162:165], v[186:189], v[4:7]
	v_mfma_f32_16x16x32_bf16 v[0:3], v[166:169], v[186:189], v[0:3]
	ds_read_b128 v[130:133], v173
	ds_read_b128 v[134:137], v173 offset:1024
	ds_read_b128 v[160:163], v173 offset:2048
	ds_read_b128 v[164:167], v173 offset:3072
	ds_read_b128 v[168:171], v128
	ds_read_b128 v[174:177], v128 offset:1024
	ds_read_b128 v[178:181], v128 offset:2048
	ds_read_b128 v[182:185], v128 offset:3072
	s_nop 0
	s_waitcnt lgkmcnt(0)
	s_nop 0
	v_mfma_f32_16x16x32_bf16 v[186:189], v[130:133], v[168:171], v[124:127]
	v_mfma_f32_16x16x32_bf16 v[120:123], v[134:137], v[168:171], v[120:123]
	v_mfma_f32_16x16x32_bf16 v[116:119], v[160:163], v[168:171], v[116:119]
	v_mfma_f32_16x16x32_bf16 v[112:115], v[164:167], v[168:171], v[112:115]
	v_mfma_f32_16x16x32_bf16 v[108:111], v[130:133], v[174:177], v[108:111]
	v_mfma_f32_16x16x32_bf16 v[104:107], v[134:137], v[174:177], v[104:107]
	v_mfma_f32_16x16x32_bf16 v[100:103], v[160:163], v[174:177], v[100:103]
	v_mfma_f32_16x16x32_bf16 v[96:99], v[164:167], v[174:177], v[96:99]
	v_mfma_f32_16x16x32_bf16 v[92:95], v[130:133], v[178:181], v[92:95]
	v_mfma_f32_16x16x32_bf16 v[88:91], v[134:137], v[178:181], v[88:91]
	v_mfma_f32_16x16x32_bf16 v[84:87], v[160:163], v[178:181], v[84:87]
	v_mfma_f32_16x16x32_bf16 v[80:83], v[164:167], v[178:181], v[80:83]
	ds_read_b128 v[124:127], v128 offset:4096
	ds_read_b128 v[168:171], v128 offset:5120
	ds_read_b128 v[174:177], v128 offset:6144
	ds_read_b128 v[178:181], v128 offset:7168
	s_waitcnt lgkmcnt(0)
	s_barrier
	v_mfma_f32_16x16x32_bf16 v[76:79], v[130:133], v[182:185], v[76:79]
	v_mfma_f32_16x16x32_bf16 v[72:75], v[134:137], v[182:185], v[72:75]
	v_mfma_f32_16x16x32_bf16 v[68:71], v[160:163], v[182:185], v[68:71]
	v_mfma_f32_16x16x32_bf16 v[64:67], v[164:167], v[182:185], v[64:67]
	v_mfma_f32_16x16x32_bf16 v[60:63], v[130:133], v[124:127], v[60:63]
	v_mfma_f32_16x16x32_bf16 v[56:59], v[134:137], v[124:127], v[56:59]
	v_mfma_f32_16x16x32_bf16 v[52:55], v[160:163], v[124:127], v[52:55]
	v_mfma_f32_16x16x32_bf16 v[48:51], v[164:167], v[124:127], v[48:51]
	v_mfma_f32_16x16x32_bf16 v[44:47], v[130:133], v[168:171], v[44:47]
	v_mfma_f32_16x16x32_bf16 v[40:43], v[134:137], v[168:171], v[40:43]
	v_mfma_f32_16x16x32_bf16 v[36:39], v[160:163], v[168:171], v[36:39]
	v_mfma_f32_16x16x32_bf16 v[32:35], v[164:167], v[168:171], v[32:35]
	v_mfma_f32_16x16x32_bf16 v[28:31], v[130:133], v[174:177], v[28:31]
	v_mfma_f32_16x16x32_bf16 v[24:27], v[134:137], v[174:177], v[24:27]
	v_mfma_f32_16x16x32_bf16 v[20:23], v[160:163], v[174:177], v[20:23]
	v_mfma_f32_16x16x32_bf16 v[16:19], v[164:167], v[174:177], v[16:19]
	v_mfma_f32_16x16x32_bf16 v[12:15], v[130:133], v[178:181], v[12:15]
	v_cndmask_b32_e64 v132, 1.0, v156, s[8:9]
	v_mul_f32_e32 v124, v132, v159
	v_pk_mul_f32 v[126:127], v[124:125], v[188:189] op_sel_hi:[0,1]
	v_mfma_f32_16x16x32_bf16 v[8:11], v[134:137], v[178:181], v[8:11]
	v_mul_f32_e64 v130, v124, v186
	v_mul_f32_e64 v131, v124, v187
	v_mfma_f32_16x16x32_bf16 v[4:7], v[160:163], v[178:181], v[4:7]
	v_mfma_f32_16x16x32_bf16 v[0:3], v[164:167], v[178:181], v[0:3]
	s_cbranch_vccz .LBB0_809
	v_mul_f32_e32 v125, 0xbfb8aa3b, v130
	v_exp_f32_e32 v125, v125
	v_mul_f32_e32 v133, 0xbfb8aa3b, v126
	v_mul_f32_e32 v128, 0xbfb8aa3b, v131
	v_exp_f32_e32 v128, v128
	v_add_f32_e32 v125, 1.0, v125
	v_rcp_f32_e32 v134, v125
	v_exp_f32_e32 v125, v133
	v_mul_f32_e32 v133, 0xbfb8aa3b, v127
	v_exp_f32_e32 v133, v133
	v_add_f32_e32 v128, 1.0, v128
	v_add_f32_e32 v125, 1.0, v125
	v_rcp_f32_e32 v136, v125
	v_add_f32_e32 v125, 1.0, v133
	v_rcp_f32_e32 v137, v125
	v_rcp_f32_e32 v135, v128
	v_pk_mul_f32 v[126:127], v[126:127], v[136:137]
	v_pk_mul_f32 v[130:131], v[130:131], v[134:135]

.LBB0_874:
	s_add_i32 s8, s5, 0xfffe8000
	s_and_b32 s9, s5, 0x18000
	s_waitcnt vmcnt(8)
	s_barrier
	s_and_b32 s8, s8, 0x18000
	s_add_i32 s9, s4, s9
	v_add_u32_e32 v128, s8, v141
	v_or_b32_e32 v143, s8, v142
	s_add_i32 s11, s9, 0x400
	s_add_i32 s10, s9, 0x800
	s_add_i32 s8, s9, 0xc00
	s_add_i32 s5, s5, 0x8000
	s_cmp_eq_u32 s5, 0x100000
	ds_read_b128 v[174:177], v128
	ds_read_b128 v[144:147], v143
	ds_read_b128 v[158:161], v143 offset:1024
	ds_read_b128 v[162:165], v143 offset:2048
	ds_read_b128 v[166:169], v143 offset:3072
	ds_read_b128 v[178:181], v128 offset:1024
	ds_read_b128 v[182:185], v128 offset:2048
	ds_read_b128 v[186:189], v128 offset:3072
	s_waitcnt lgkmcnt(6)
	v_mfma_f32_16x16x32_bf16 v[124:127], v[174:177], v[144:147], v[124:127]
	s_waitcnt lgkmcnt(5)
	v_mfma_f32_16x16x32_bf16 v[120:123], v[174:177], v[158:161], v[120:123]
	s_waitcnt lgkmcnt(4)
	v_mfma_f32_16x16x32_bf16 v[116:119], v[174:177], v[162:165], v[116:119]
	s_waitcnt lgkmcnt(3)
	s_mov_b32 m0, s9
	v_mfma_f32_16x16x32_bf16 v[112:115], v[174:177], v[166:169], v[112:115]
	global_load_lds_dwordx4 v[136:137], off
	v_lshl_add_u64 v[136:137], v[136:137], 0, 64
	s_waitcnt lgkmcnt(2)
	v_mfma_f32_16x16x32_bf16 v[108:111], v[178:181], v[144:147], v[108:111]
	ds_read_b128 v[174:177], v128 offset:4096
	v_mfma_f32_16x16x32_bf16 v[104:107], v[178:181], v[158:161], v[104:107]
	v_mfma_f32_16x16x32_bf16 v[100:103], v[178:181], v[162:165], v[100:103]
	s_mov_b32 m0, s11
	v_mfma_f32_16x16x32_bf16 v[96:99], v[178:181], v[166:169], v[96:99]
	global_load_lds_dwordx4 v[134:135], off
	v_lshl_add_u64 v[134:135], v[134:135], 0, 64
	s_waitcnt lgkmcnt(2)
	v_mfma_f32_16x16x32_bf16 v[92:95], v[182:185], v[144:147], v[92:95]
	ds_read_b128 v[178:181], v128 offset:5120
	v_mfma_f32_16x16x32_bf16 v[88:91], v[182:185], v[158:161], v[88:91]
	v_mfma_f32_16x16x32_bf16 v[84:87], v[182:185], v[162:165], v[84:87]
	s_mov_b32 m0, s10
	v_mfma_f32_16x16x32_bf16 v[80:83], v[182:185], v[166:169], v[80:83]
	global_load_lds_dwordx4 v[132:133], off
	v_lshl_add_u64 v[132:133], v[132:133], 0, 64
	s_waitcnt lgkmcnt(2)
	v_mfma_f32_16x16x32_bf16 v[76:79], v[186:189], v[144:147], v[76:79]
	ds_read_b128 v[182:185], v128 offset:6144
	v_mfma_f32_16x16x32_bf16 v[72:75], v[186:189], v[158:161], v[72:75]
	v_mfma_f32_16x16x32_bf16 v[68:71], v[186:189], v[162:165], v[68:71]
	s_mov_b32 m0, s8
	v_mfma_f32_16x16x32_bf16 v[64:67], v[186:189], v[166:169], v[64:67]
	global_load_lds_dwordx4 v[130:131], off
	v_lshl_add_u64 v[130:131], v[130:131], 0, 64
	s_waitcnt lgkmcnt(2)
	v_mfma_f32_16x16x32_bf16 v[60:63], v[174:177], v[144:147], v[60:63]
	ds_read_b128 v[186:189], v128 offset:7168
	v_mfma_f32_16x16x32_bf16 v[56:59], v[174:177], v[158:161], v[56:59]
	v_mfma_f32_16x16x32_bf16 v[52:55], v[174:177], v[162:165], v[52:55]
	v_mfma_f32_16x16x32_bf16 v[48:51], v[174:177], v[166:169], v[48:51]
	s_waitcnt lgkmcnt(2)
	v_mfma_f32_16x16x32_bf16 v[44:47], v[178:181], v[144:147], v[44:47]
	v_mfma_f32_16x16x32_bf16 v[40:43], v[178:181], v[158:161], v[40:43]
	v_mfma_f32_16x16x32_bf16 v[36:39], v[178:181], v[162:165], v[36:39]
	v_mfma_f32_16x16x32_bf16 v[32:35], v[178:181], v[166:169], v[32:35]
	s_waitcnt lgkmcnt(1)
	v_mfma_f32_16x16x32_bf16 v[28:31], v[182:185], v[144:147], v[28:31]
	v_mfma_f32_16x16x32_bf16 v[24:27], v[182:185], v[158:161], v[24:27]
	v_mfma_f32_16x16x32_bf16 v[20:23], v[182:185], v[162:165], v[20:23]
	v_mfma_f32_16x16x32_bf16 v[16:19], v[182:185], v[166:169], v[16:19]
	s_waitcnt lgkmcnt(0)
	v_mfma_f32_16x16x32_bf16 v[12:15], v[186:189], v[144:147], v[12:15]
	v_mfma_f32_16x16x32_bf16 v[8:11], v[186:189], v[158:161], v[8:11]
	v_mfma_f32_16x16x32_bf16 v[4:7], v[186:189], v[162:165], v[4:7]
	v_mfma_f32_16x16x32_bf16 v[0:3], v[186:189], v[166:169], v[0:3]
	s_cbranch_scc0 .LBB0_874
	s_waitcnt vmcnt(8)
	s_barrier
	v_add_u32_e32 v128, 0x8000, v141
	v_or_b32_e32 v143, 0x8000, v142
	ds_read_b128 v[130:133], v143
	ds_read_b128 v[134:137], v143 offset:1024
	ds_read_b128 v[144:147], v143 offset:2048
	ds_read_b128 v[158:161], v143 offset:3072
	ds_read_b128 v[162:165], v128
	ds_read_b128 v[166:169], v128 offset:1024
	ds_read_b128 v[174:177], v128 offset:2048
	ds_read_b128 v[178:181], v128 offset:3072
	v_or_b32_e32 v143, 0x10000, v142
	s_waitcnt lgkmcnt(0)
	s_ashr_i32 s13, s12, 31
	v_mfma_f32_16x16x32_bf16 v[124:127], v[162:165], v[130:133], v[124:127]
	s_lshl_b64 s[4:5], s[12:13], 2
	s_add_u32 s4, s62, s4
	s_addc_u32 s5, s63, s5
	v_mfma_f32_16x16x32_bf16 v[120:123], v[162:165], v[134:137], v[120:123]
	v_mfma_f32_16x16x32_bf16 v[116:119], v[162:165], v[144:147], v[116:119]
	v_mfma_f32_16x16x32_bf16 v[112:115], v[162:165], v[158:161], v[112:115]
	v_mfma_f32_16x16x32_bf16 v[108:111], v[166:169], v[130:133], v[108:111]
	v_mfma_f32_16x16x32_bf16 v[104:107], v[166:169], v[134:137], v[104:107]
	v_mfma_f32_16x16x32_bf16 v[100:103], v[166:169], v[144:147], v[100:103]
	v_mfma_f32_16x16x32_bf16 v[96:99], v[166:169], v[158:161], v[96:99]
	v_mfma_f32_16x16x32_bf16 v[92:95], v[174:177], v[130:133], v[92:95]
	v_mfma_f32_16x16x32_bf16 v[88:91], v[174:177], v[134:137], v[88:91]
	v_mfma_f32_16x16x32_bf16 v[84:87], v[174:177], v[144:147], v[84:87]
	v_mfma_f32_16x16x32_bf16 v[80:83], v[174:177], v[158:161], v[80:83]
	v_mfma_f32_16x16x32_bf16 v[76:79], v[178:181], v[130:133], v[76:79]
	v_mfma_f32_16x16x32_bf16 v[72:75], v[178:181], v[134:137], v[72:75]
	v_mfma_f32_16x16x32_bf16 v[68:71], v[178:181], v[144:147], v[68:71]
	v_mfma_f32_16x16x32_bf16 v[64:67], v[178:181], v[158:161], v[64:67]
	ds_read_b128 v[162:165], v128 offset:4096
	ds_read_b128 v[166:169], v128 offset:5120
	ds_read_b128 v[174:177], v128 offset:6144
	ds_read_b128 v[178:181], v128 offset:7168
	s_waitcnt lgkmcnt(0)
	s_waitcnt vmcnt(4)
	s_barrier
	v_mfma_f32_16x16x32_bf16 v[60:63], v[162:165], v[130:133], v[60:63]
	v_add_u32_e32 v128, 0x10000, v141
	v_mfma_f32_16x16x32_bf16 v[56:59], v[162:165], v[134:137], v[56:59]
	v_mfma_f32_16x16x32_bf16 v[52:55], v[162:165], v[144:147], v[52:55]
	v_mfma_f32_16x16x32_bf16 v[48:51], v[162:165], v[158:161], v[48:51]
	v_mfma_f32_16x16x32_bf16 v[44:47], v[166:169], v[130:133], v[44:47]
	v_mfma_f32_16x16x32_bf16 v[40:43], v[166:169], v[134:137], v[40:43]
	v_mfma_f32_16x16x32_bf16 v[36:39], v[166:169], v[144:147], v[36:39]
	v_mfma_f32_16x16x32_bf16 v[32:35], v[166:169], v[158:161], v[32:35]
	v_mfma_f32_16x16x32_bf16 v[28:31], v[174:177], v[130:133], v[28:31]
	v_mfma_f32_16x16x32_bf16 v[24:27], v[174:177], v[134:137], v[24:27]
	v_mfma_f32_16x16x32_bf16 v[20:23], v[174:177], v[144:147], v[20:23]
	v_mfma_f32_16x16x32_bf16 v[16:19], v[174:177], v[158:161], v[16:19]
	v_mfma_f32_16x16x32_bf16 v[12:15], v[178:181], v[130:133], v[12:15]
	v_mfma_f32_16x16x32_bf16 v[8:11], v[178:181], v[134:137], v[8:11]
	v_mfma_f32_16x16x32_bf16 v[4:7], v[178:181], v[144:147], v[4:7]
	v_mfma_f32_16x16x32_bf16 v[0:3], v[178:181], v[158:161], v[0:3]
	ds_read_b128 v[130:133], v143
	ds_read_b128 v[134:137], v143 offset:1024
	ds_read_b128 v[144:147], v143 offset:2048
	ds_read_b128 v[158:161], v143 offset:3072
	ds_read_b128 v[162:165], v128
	ds_read_b128 v[166:169], v128 offset:1024
	ds_read_b128 v[174:177], v128 offset:2048
	ds_read_b128 v[178:181], v128 offset:3072
	s_nop 0
	s_waitcnt lgkmcnt(0)
	s_nop 0
	v_mfma_f32_16x16x32_bf16 v[124:127], v[162:165], v[130:133], v[124:127]
	v_mfma_f32_16x16x32_bf16 v[120:123], v[162:165], v[134:137], v[120:123]
	v_mfma_f32_16x16x32_bf16 v[116:119], v[162:165], v[144:147], v[116:119]
	v_mfma_f32_16x16x32_bf16 v[112:115], v[162:165], v[158:161], v[112:115]
	v_mfma_f32_16x16x32_bf16 v[108:111], v[166:169], v[130:133], v[108:111]
	v_mfma_f32_16x16x32_bf16 v[104:107], v[166:169], v[134:137], v[104:107]
	v_mfma_f32_16x16x32_bf16 v[100:103], v[166:169], v[144:147], v[100:103]
	v_mfma_f32_16x16x32_bf16 v[96:99], v[166:169], v[158:161], v[96:99]
	v_mfma_f32_16x16x32_bf16 v[92:95], v[174:177], v[130:133], v[92:95]
	v_mfma_f32_16x16x32_bf16 v[88:91], v[174:177], v[134:137], v[88:91]
	v_mfma_f32_16x16x32_bf16 v[84:87], v[174:177], v[144:147], v[84:87]
	v_mfma_f32_16x16x32_bf16 v[80:83], v[174:177], v[158:161], v[80:83]
	v_mfma_f32_16x16x32_bf16 v[76:79], v[178:181], v[130:133], v[76:79]
	v_mfma_f32_16x16x32_bf16 v[72:75], v[178:181], v[134:137], v[72:75]
	v_mfma_f32_16x16x32_bf16 v[68:71], v[178:181], v[144:147], v[68:71]
	v_mfma_f32_16x16x32_bf16 v[64:67], v[178:181], v[158:161], v[64:67]
	ds_read_b128 v[162:165], v128 offset:4096
	ds_read_b128 v[166:169], v128 offset:5120
	ds_read_b128 v[174:177], v128 offset:6144
	ds_read_b128 v[178:181], v128 offset:7168
	s_waitcnt lgkmcnt(0)
	s_waitcnt vmcnt(0)
	s_barrier
	v_mfma_f32_16x16x32_bf16 v[60:63], v[162:165], v[130:133], v[60:63]
	v_add_u32_e32 v128, 0x18000, v141
	v_or_b32_e32 v141, 0x18000, v142
	v_mfma_f32_16x16x32_bf16 v[56:59], v[162:165], v[134:137], v[56:59]
	v_mfma_f32_16x16x32_bf16 v[52:55], v[162:165], v[144:147], v[52:55]
	v_mfma_f32_16x16x32_bf16 v[48:51], v[162:165], v[158:161], v[48:51]
	v_mfma_f32_16x16x32_bf16 v[44:47], v[166:169], v[130:133], v[44:47]
	v_mfma_f32_16x16x32_bf16 v[40:43], v[166:169], v[134:137], v[40:43]
	v_mfma_f32_16x16x32_bf16 v[36:39], v[166:169], v[144:147], v[36:39]
	v_mfma_f32_16x16x32_bf16 v[32:35], v[166:169], v[158:161], v[32:35]
	v_mfma_f32_16x16x32_bf16 v[28:31], v[174:177], v[130:133], v[28:31]
	v_mfma_f32_16x16x32_bf16 v[24:27], v[174:177], v[134:137], v[24:27]
	v_mfma_f32_16x16x32_bf16 v[20:23], v[174:177], v[144:147], v[20:23]
	v_mfma_f32_16x16x32_bf16 v[16:19], v[174:177], v[158:161], v[16:19]
	v_mfma_f32_16x16x32_bf16 v[12:15], v[178:181], v[130:133], v[12:15]
	v_mfma_f32_16x16x32_bf16 v[8:11], v[178:181], v[134:137], v[8:11]
	v_mfma_f32_16x16x32_bf16 v[4:7], v[178:181], v[144:147], v[4:7]
	v_mfma_f32_16x16x32_bf16 v[0:3], v[178:181], v[158:161], v[0:3]
	ds_read_b128 v[130:133], v141
	ds_read_b128 v[134:137], v141 offset:1024
	ds_read_b128 v[142:145], v141 offset:2048
	ds_read_b128 v[158:161], v141 offset:3072
	ds_read_b128 v[162:165], v128
	ds_read_b128 v[166:169], v128 offset:1024
	ds_read_b128 v[174:177], v128 offset:2048
	ds_read_b128 v[178:181], v128 offset:3072
	s_nop 0
	s_waitcnt lgkmcnt(0)
	s_nop 0
	v_mfma_f32_16x16x32_bf16 v[124:127], v[162:165], v[130:133], v[124:127]
	v_mfma_f32_16x16x32_bf16 v[120:123], v[162:165], v[134:137], v[120:123]
	v_mfma_f32_16x16x32_bf16 v[116:119], v[162:165], v[142:145], v[116:119]
	v_mfma_f32_16x16x32_bf16 v[162:165], v[162:165], v[158:161], v[112:115]
	v_mfma_f32_16x16x32_bf16 v[108:111], v[166:169], v[130:133], v[108:111]
	v_mfma_f32_16x16x32_bf16 v[104:107], v[166:169], v[134:137], v[104:107]
	v_mfma_f32_16x16x32_bf16 v[100:103], v[166:169], v[142:145], v[100:103]
	v_mfma_f32_16x16x32_bf16 v[96:99], v[166:169], v[158:161], v[96:99]
	v_mfma_f32_16x16x32_bf16 v[92:95], v[174:177], v[130:133], v[92:95]
	v_mfma_f32_16x16x32_bf16 v[88:91], v[174:177], v[134:137], v[88:91]
	v_mfma_f32_16x16x32_bf16 v[84:87], v[174:177], v[142:145], v[84:87]
	v_mfma_f32_16x16x32_bf16 v[80:83], v[174:177], v[158:161], v[80:83]
	v_mfma_f32_16x16x32_bf16 v[76:79], v[178:181], v[130:133], v[76:79]
	v_mfma_f32_16x16x32_bf16 v[72:75], v[178:181], v[134:137], v[72:75]
	v_mfma_f32_16x16x32_bf16 v[68:71], v[178:181], v[142:145], v[68:71]
	v_mfma_f32_16x16x32_bf16 v[64:67], v[178:181], v[158:161], v[64:67]
	ds_read_b128 v[112:115], v128 offset:4096
	ds_read_b128 v[166:169], v128 offset:5120
	ds_read_b128 v[174:177], v128 offset:6144
	ds_read_b128 v[178:181], v128 offset:7168
	s_waitcnt lgkmcnt(0)
	s_barrier
	v_mfma_f32_16x16x32_bf16 v[60:63], v[112:115], v[130:133], v[60:63]
	v_mfma_f32_16x16x32_bf16 v[56:59], v[112:115], v[134:137], v[56:59]
	v_mfma_f32_16x16x32_bf16 v[52:55], v[112:115], v[142:145], v[52:55]
	v_mfma_f32_16x16x32_bf16 v[48:51], v[112:115], v[158:161], v[48:51]
	v_lshlrev_b32_e32 v114, 3, v139
	v_lshlrev_b32_e32 v113, 8, v140
	v_and_b32_e32 v114, 8, v114
	v_add3_u32 v113, s38, v113, v114
	v_lshlrev_b32_e32 v114, 4, v139
	v_mfma_f32_16x16x32_bf16 v[44:47], v[166:169], v[130:133], v[44:47]
	v_lshrrev_b32_e32 v112, 5, v138
	v_xor_b32_e32 v115, v112, v140
	v_lshl_add_u32 v115, v115, 4, v113
	v_mfma_f32_16x16x32_bf16 v[28:31], v[174:177], v[130:133], v[28:31]
	v_mfma_f32_16x16x32_bf16 v[12:15], v[178:181], v[130:133], v[12:15]
	global_load_dwordx4 v[130:133], v114, s[4:5]
	s_waitcnt vmcnt(0)
	v_pk_mul_f32 v[126:127], v[126:127], v[132:133]
	v_pk_mul_f32 v[124:125], v[124:125], v[130:131]
	v_pk_mul_f32 v[122:123], v[122:123], v[132:133]
	v_pk_mul_f32 v[120:121], v[120:121], v[130:131]
	v_cvt_pk_bf16_f32 v124, v124, v125
	v_cvt_pk_bf16_f32 v125, v126, v127
	v_cvt_pk_bf16_f32 v120, v120, v121
	v_cvt_pk_bf16_f32 v121, v122, v123
	v_pk_mul_f32 v[118:119], v[118:119], v[132:133]
	v_pk_mul_f32 v[116:117], v[116:117], v[130:131]
	ds_write2st64_b64 v115, v[124:125], v[120:121] offset1:8
	v_cvt_pk_bf16_f32 v116, v116, v117
	v_cvt_pk_bf16_f32 v117, v118, v119
	v_pk_mul_f32 v[118:119], v[164:165], v[132:133]
	v_pk_mul_f32 v[120:121], v[162:163], v[130:131]
	v_mfma_f32_16x16x32_bf16 v[36:39], v[166:169], v[142:145], v[36:39]
	v_cvt_pk_bf16_f32 v120, v120, v121
	v_cvt_pk_bf16_f32 v121, v118, v119
	ds_write2st64_b64 v115, v[116:117], v[120:121] offset0:16 offset1:24
	global_load_dwordx4 v[116:119], v114, s[4:5] offset:64
	v_bitop3_b32 v115, v112, v140, 2 bitop3:0x36
	v_lshl_add_u32 v115, v115, 4, v113
	v_mfma_f32_16x16x32_bf16 v[32:35], v[166:169], v[158:161], v[32:35]
	s_waitcnt vmcnt(0)
	v_pk_mul_f32 v[102:103], v[102:103], v[118:119]
	v_pk_mul_f32 v[100:101], v[100:101], v[116:117]
	v_pk_mul_f32 v[98:99], v[98:99], v[118:119]
	v_pk_mul_f32 v[96:97], v[96:97], v[116:117]
	v_cvt_pk_bf16_f32 v100, v100, v101
	v_cvt_pk_bf16_f32 v101, v102, v103
	v_cvt_pk_bf16_f32 v96, v96, v97
	v_cvt_pk_bf16_f32 v97, v98, v99
	ds_write2st64_b64 v115, v[100:101], v[96:97] offset0:16 offset1:24
	global_load_dwordx4 v[96:99], v114, s[4:5] offset:128
	v_bitop3_b32 v100, v112, v140, 4 bitop3:0x36
	v_lshl_add_u32 v100, v100, 4, v113
	v_mfma_f32_16x16x32_bf16 v[20:23], v[174:177], v[142:145], v[20:23]
	v_mul_f32_e64 v110, v110, v118
	v_mul_f32_e64 v111, v111, v119
	v_pk_mul_f32 v[108:109], v[108:109], v[116:117]
	v_pk_mul_f32 v[106:107], v[106:107], v[118:119]
	v_mfma_f32_16x16x32_bf16 v[16:19], v[174:177], v[158:161], v[16:19]
	v_mul_f32_e64 v104, v104, v116
	v_mul_f32_e64 v105, v105, v117
	v_cvt_pk_bf16_f32 v108, v108, v109
	v_cvt_pk_bf16_f32 v109, v110, v111
	v_mfma_f32_16x16x32_bf16 v[0:3], v[178:181], v[158:161], v[0:3]
	v_cvt_pk_bf16_f32 v104, v104, v105
	v_cvt_pk_bf16_f32 v105, v106, v107
	ds_write2st64_b64 v115, v[108:109], v[104:105] offset1:8
	v_mfma_f32_16x16x32_bf16 v[8:11], v[178:181], v[134:137], v[8:11]
	s_waitcnt vmcnt(0)
	v_pk_mul_f32 v[86:87], v[86:87], v[98:99]
	v_pk_mul_f32 v[84:85], v[84:85], v[96:97]
	v_pk_mul_f32 v[82:83], v[82:83], v[98:99]
	v_pk_mul_f32 v[80:81], v[80:81], v[96:97]
	v_cvt_pk_bf16_f32 v84, v84, v85
	v_cvt_pk_bf16_f32 v85, v86, v87
	v_cvt_pk_bf16_f32 v80, v80, v81
	v_cvt_pk_bf16_f32 v81, v82, v83
	ds_write2st64_b64 v100, v[84:85], v[80:81] offset0:16 offset1:24
	global_load_dwordx4 v[80:83], v114, s[4:5] offset:192
	v_bitop3_b32 v84, v112, v140, 6 bitop3:0x36
	v_lshl_add_u32 v84, v84, 4, v113
	v_mfma_f32_16x16x32_bf16 v[40:43], v[166:169], v[134:137], v[40:43]
	v_mul_f32_e64 v94, v94, v98
	v_mul_f32_e64 v95, v95, v99
	v_pk_mul_f32 v[92:93], v[92:93], v[96:97]
	v_pk_mul_f32 v[90:91], v[90:91], v[98:99]
	v_mfma_f32_16x16x32_bf16 v[24:27], v[174:177], v[134:137], v[24:27]
	v_mul_f32_e64 v88, v88, v96
	v_mul_f32_e64 v89, v89, v97
	v_cvt_pk_bf16_f32 v92, v92, v93
	v_cvt_pk_bf16_f32 v93, v94, v95
	v_mfma_f32_16x16x32_bf16 v[4:7], v[178:181], v[142:145], v[4:7]
	v_cvt_pk_bf16_f32 v88, v88, v89
	v_cvt_pk_bf16_f32 v89, v90, v91
	ds_write2st64_b64 v100, v[92:93], v[88:89] offset1:8
	s_waitcnt vmcnt(0)
	v_pk_mul_f32 v[70:71], v[70:71], v[82:83]
	v_pk_mul_f32 v[68:69], v[68:69], v[80:81]
	v_pk_mul_f32 v[66:67], v[66:67], v[82:83]
	v_pk_mul_f32 v[64:65], v[64:65], v[80:81]
	v_cvt_pk_bf16_f32 v68, v68, v69
	v_cvt_pk_bf16_f32 v69, v70, v71
	v_cvt_pk_bf16_f32 v64, v64, v65
	v_cvt_pk_bf16_f32 v65, v66, v67
	ds_write2st64_b64 v84, v[68:69], v[64:65] offset0:16 offset1:24
	global_load_dwordx4 v[64:67], v114, s[4:5] offset:256
	v_bitop3_b32 v68, v112, v140, 8 bitop3:0x36
	v_lshl_add_u32 v68, v68, 4, v113
	v_pk_mul_f32 v[78:79], v[78:79], v[82:83]
	v_pk_mul_f32 v[76:77], v[76:77], v[80:81]
	v_pk_mul_f32 v[74:75], v[74:75], v[82:83]
	v_pk_mul_f32 v[72:73], v[72:73], v[80:81]
	v_cvt_pk_bf16_f32 v76, v76, v77
	v_cvt_pk_bf16_f32 v77, v78, v79
	v_cvt_pk_bf16_f32 v72, v72, v73
	v_cvt_pk_bf16_f32 v73, v74, v75
	ds_write2st64_b64 v84, v[76:77], v[72:73] offset1:8
	s_waitcnt vmcnt(0)
	v_pk_mul_f32 v[54:55], v[54:55], v[66:67]
	v_pk_mul_f32 v[52:53], v[52:53], v[64:65]
	v_pk_mul_f32 v[50:51], v[50:51], v[66:67]
	v_pk_mul_f32 v[48:49], v[48:49], v[64:65]
	v_cvt_pk_bf16_f32 v52, v52, v53
	v_cvt_pk_bf16_f32 v53, v54, v55
	v_cvt_pk_bf16_f32 v48, v48, v49
	v_cvt_pk_bf16_f32 v49, v50, v51
	ds_write2st64_b64 v68, v[52:53], v[48:49] offset0:16 offset1:24
	global_load_dwordx4 v[48:51], v114, s[4:5] offset:320
	v_bitop3_b32 v52, v112, v140, 10 bitop3:0x36
	v_lshl_add_u32 v52, v52, 4, v113
	v_pk_mul_f32 v[62:63], v[62:63], v[66:67]
	v_pk_mul_f32 v[60:61], v[60:61], v[64:65]
	v_pk_mul_f32 v[58:59], v[58:59], v[66:67]
	v_pk_mul_f32 v[56:57], v[56:57], v[64:65]
	v_cvt_pk_bf16_f32 v60, v60, v61
	v_cvt_pk_bf16_f32 v61, v62, v63
	v_cvt_pk_bf16_f32 v56, v56, v57
	v_cvt_pk_bf16_f32 v57, v58, v59
	ds_write2st64_b64 v68, v[60:61], v[56:57] offset1:8
	s_waitcnt vmcnt(0)
	v_pk_mul_f32 v[38:39], v[38:39], v[50:51]
	v_pk_mul_f32 v[36:37], v[36:37], v[48:49]
	v_pk_mul_f32 v[34:35], v[34:35], v[50:51]
	v_pk_mul_f32 v[32:33], v[32:33], v[48:49]
	v_cvt_pk_bf16_f32 v36, v36, v37
	v_cvt_pk_bf16_f32 v37, v38, v39
	v_cvt_pk_bf16_f32 v32, v32, v33
	v_cvt_pk_bf16_f32 v33, v34, v35
	ds_write2st64_b64 v52, v[36:37], v[32:33] offset0:16 offset1:24
	global_load_dwordx4 v[32:35], v114, s[4:5] offset:384
	v_bitop3_b32 v36, v112, v140, 12 bitop3:0x36
	v_lshl_add_u32 v36, v36, 4, v113
	v_pk_mul_f32 v[46:47], v[46:47], v[50:51]
	v_pk_mul_f32 v[44:45], v[44:45], v[48:49]
	v_pk_mul_f32 v[42:43], v[42:43], v[50:51]
	v_pk_mul_f32 v[40:41], v[40:41], v[48:49]
	v_cvt_pk_bf16_f32 v44, v44, v45
	v_cvt_pk_bf16_f32 v45, v46, v47
	v_cvt_pk_bf16_f32 v40, v40, v41
	v_cvt_pk_bf16_f32 v41, v42, v43
	ds_write2st64_b64 v52, v[44:45], v[40:41] offset1:8
	s_waitcnt vmcnt(0)
	v_pk_mul_f32 v[22:23], v[22:23], v[34:35]
	v_pk_mul_f32 v[20:21], v[20:21], v[32:33]
	v_pk_mul_f32 v[18:19], v[18:19], v[34:35]
	v_pk_mul_f32 v[16:17], v[16:17], v[32:33]
	v_cvt_pk_bf16_f32 v20, v20, v21
	v_cvt_pk_bf16_f32 v21, v22, v23
	v_cvt_pk_bf16_f32 v16, v16, v17
	v_cvt_pk_bf16_f32 v17, v18, v19
	ds_write2st64_b64 v36, v[20:21], v[16:17] offset0:16 offset1:24
	global_load_dwordx4 v[16:19], v114, s[4:5] offset:448
	s_lshr_b32 s4, s40, 6
	s_and_b32 s5, s39, -16
	s_or_b32 s4, s4, s5
	v_bitop3_b32 v20, v112, v140, 14 bitop3:0x36
	s_ashr_i32 s5, s4, 31
	v_pk_mul_f32 v[30:31], v[30:31], v[34:35]
	v_pk_mul_f32 v[28:29], v[28:29], v[32:33]
	v_pk_mul_f32 v[26:27], v[26:27], v[34:35]
	v_pk_mul_f32 v[24:25], v[24:25], v[32:33]
	v_lshl_add_u32 v20, v20, 4, v113
	s_lshl_b64 s[4:5], s[4:5], 19
	v_cvt_pk_bf16_f32 v28, v28, v29
	v_cvt_pk_bf16_f32 v29, v30, v31
	v_cvt_pk_bf16_f32 v24, v24, v25
	v_cvt_pk_bf16_f32 v25, v26, v27
	s_add_u32 s4, s26, s4
	ds_write2st64_b64 v36, v[28:29], v[24:25] offset1:8
	s_addc_u32 s5, s27, s5
	s_and_b32 s8, s12, 0xf80
	s_lshl_b32 s8, s8, 1
	s_add_u32 s4, s4, s8
	s_addc_u32 s5, s5, 0
	s_waitcnt vmcnt(0)
	v_pk_mul_f32 v[2:3], v[2:3], v[18:19]
	v_pk_mul_f32 v[0:1], v[0:1], v[16:17]
	v_pk_mul_f32 v[14:15], v[14:15], v[18:19]
	v_pk_mul_f32 v[12:13], v[12:13], v[16:17]
	v_pk_mul_f32 v[10:11], v[10:11], v[18:19]
	v_pk_mul_f32 v[8:9], v[8:9], v[16:17]
	v_cvt_pk_bf16_f32 v0, v0, v1
	v_cvt_pk_bf16_f32 v1, v2, v3
	v_xor_b32_e32 v3, v139, v138
	v_cvt_pk_bf16_f32 v12, v12, v13
	v_cvt_pk_bf16_f32 v13, v14, v15
	v_cvt_pk_bf16_f32 v8, v8, v9
	v_cvt_pk_bf16_f32 v9, v10, v11
	v_lshlrev_b32_e32 v3, 4, v3
	ds_write2st64_b64 v20, v[12:13], v[8:9] offset1:8
	v_pk_mul_f32 v[6:7], v[6:7], v[18:19]
	v_pk_mul_f32 v[4:5], v[4:5], v[16:17]
	v_lshlrev_b32_e32 v2, 8, v139
	v_and_b32_e32 v8, 0xf0, v3
	v_cvt_pk_bf16_f32 v4, v4, v5
	v_cvt_pk_bf16_f32 v5, v6, v7
	v_add3_u32 v2, s38, v2, v8
	ds_write2st64_b64 v20, v[4:5], v[0:1] offset0:16 offset1:24
	ds_read_b128 v[2:5], v2
	v_lshlrev_b32_e32 v0, 4, v138
	v_and_b32_e32 v128, 0xf0, v0
	v_lshl_add_u64 v[0:1], s[4:5], 0, v[128:129]
	v_lshlrev_b32_e32 v128, 13, v139
	v_lshl_add_u64 v[6:7], v[0:1], 0, v[128:129]
	s_waitcnt lgkmcnt(0)
	global_store_dwordx4 v[6:7], v[2:5], off
	v_or_b32_e32 v6, 4, v139
	v_lshlrev_b32_e32 v128, 13, v6
	v_bitop3_b32 v3, v139, v138, 4 bitop3:0x36
	v_lshlrev_b32_e32 v3, 4, v3
	v_lshlrev_b32_e32 v2, 8, v6
	v_and_b32_e32 v3, 0xf0, v3
	v_add3_u32 v2, s38, v2, v3
	ds_read_b128 v[2:5], v2
	v_lshl_add_u64 v[6:7], v[0:1], 0, v[128:129]
	s_waitcnt lgkmcnt(0)
	global_store_dwordx4 v[6:7], v[2:5], off
	s_nop 1
	v_bitop3_b32 v3, v139, v138, 8 bitop3:0x36
	v_or_b32_e32 v6, 8, v139
	v_lshlrev_b32_e32 v3, 4, v3
	v_lshlrev_b32_e32 v2, 8, v6
	v_and_b32_e32 v3, 0xf0, v3
	v_add3_u32 v2, s38, v2, v3
	ds_read_b128 v[2:5], v2
	v_lshlrev_b32_e32 v128, 13, v6
	v_lshl_add_u64 v[6:7], v[0:1], 0, v[128:129]
	s_waitcnt lgkmcnt(0)
	global_store_dwordx4 v[6:7], v[2:5], off
	s_nop 1
	v_bitop3_b32 v3, v139, v138, 12 bitop3:0x36
	v_or_b32_e32 v6, 12, v139
	v_lshlrev_b32_e32 v3, 4, v3
	v_lshlrev_b32_e32 v2, 8, v6
	v_and_b32_e32 v3, 0xf0, v3
	v_add3_u32 v2, s38, v2, v3
	ds_read_b128 v[2:5], v2
	v_lshlrev_b32_e32 v128, 13, v6
	v_lshl_add_u64 v[6:7], v[0:1], 0, v[128:129]
	s_waitcnt lgkmcnt(0)
	global_store_dwordx4 v[6:7], v[2:5], off
	v_or_b32_e32 v6, 16, v139
	s_nop 0
	v_lshlrev_b32_e32 v2, 8, v6
	v_add3_u32 v2, s38, v2, v8
	ds_read_b128 v[2:5], v2
	v_lshlrev_b32_e32 v128, 13, v6
	v_lshl_add_u64 v[6:7], v[0:1], 0, v[128:129]
	s_waitcnt lgkmcnt(0)
	global_store_dwordx4 v[6:7], v[2:5], off
	s_nop 1
	v_bitop3_b32 v3, v139, v138, 20 bitop3:0x36
	v_or_b32_e32 v6, 20, v139
	v_lshlrev_b32_e32 v3, 4, v3
	v_lshlrev_b32_e32 v2, 8, v6
	v_and_b32_e32 v3, 0xf0, v3
	v_add3_u32 v2, s38, v2, v3
	ds_read_b128 v[2:5], v2
	v_lshlrev_b32_e32 v128, 13, v6
	v_lshl_add_u64 v[6:7], v[0:1], 0, v[128:129]
	s_waitcnt lgkmcnt(0)
	global_store_dwordx4 v[6:7], v[2:5], off
	s_nop 1
	v_bitop3_b32 v3, v139, v138, 24 bitop3:0x36
	v_or_b32_e32 v6, 24, v139
	v_lshlrev_b32_e32 v3, 4, v3
	v_lshlrev_b32_e32 v2, 8, v6
	v_and_b32_e32 v3, 0xf0, v3
	v_add3_u32 v2, s38, v2, v3
	ds_read_b128 v[2:5], v2
	v_lshlrev_b32_e32 v128, 13, v6
	v_lshl_add_u64 v[6:7], v[0:1], 0, v[128:129]
	s_waitcnt lgkmcnt(0)
	global_store_dwordx4 v[6:7], v[2:5], off
	s_nop 1
	v_bitop3_b32 v3, v139, v138, 28 bitop3:0x36
	v_or_b32_e32 v6, 28, v139
	v_lshlrev_b32_e32 v3, 4, v3
	v_lshlrev_b32_e32 v2, 8, v6
	v_and_b32_e32 v3, 0xf0, v3
	v_add3_u32 v2, s38, v2, v3
	ds_read_b128 v[2:5], v2
	v_lshlrev_b32_e32 v128, 13, v6
	v_lshl_add_u64 v[6:7], v[0:1], 0, v[128:129]
	s_waitcnt lgkmcnt(0)
	global_store_dwordx4 v[6:7], v[2:5], off
	v_or_b32_e32 v6, 32, v139
	s_nop 0
	v_lshlrev_b32_e32 v2, 8, v6
	v_add3_u32 v2, s38, v2, v8
	ds_read_b128 v[2:5], v2
	v_lshlrev_b32_e32 v128, 13, v6
	v_lshl_add_u64 v[6:7], v[0:1], 0, v[128:129]
	s_waitcnt lgkmcnt(0)
	global_store_dwordx4 v[6:7], v[2:5], off
	s_nop 1
	v_bitop3_b32 v3, v139, v138, 36 bitop3:0x36
	v_or_b32_e32 v6, 36, v139
	v_lshlrev_b32_e32 v3, 4, v3
	v_lshlrev_b32_e32 v2, 8, v6
	v_and_b32_e32 v3, 0xf0, v3
	v_add3_u32 v2, s38, v2, v3
	ds_read_b128 v[2:5], v2
	v_lshlrev_b32_e32 v128, 13, v6
	v_lshl_add_u64 v[6:7], v[0:1], 0, v[128:129]
	s_waitcnt lgkmcnt(0)
	global_store_dwordx4 v[6:7], v[2:5], off
	s_nop 1
	v_bitop3_b32 v3, v139, v138, 40 bitop3:0x36
	v_or_b32_e32 v6, 40, v139
	v_lshlrev_b32_e32 v3, 4, v3
	v_lshlrev_b32_e32 v2, 8, v6
	v_and_b32_e32 v3, 0xf0, v3
	v_add3_u32 v2, s38, v2, v3
	ds_read_b128 v[2:5], v2
	v_lshlrev_b32_e32 v128, 13, v6
	v_lshl_add_u64 v[6:7], v[0:1], 0, v[128:129]
	s_waitcnt lgkmcnt(0)
	global_store_dwordx4 v[6:7], v[2:5], off
	s_nop 1
	v_bitop3_b32 v3, v139, v138, 44 bitop3:0x36
	v_or_b32_e32 v6, 44, v139
	v_lshlrev_b32_e32 v3, 4, v3
	v_lshlrev_b32_e32 v2, 8, v6
	v_and_b32_e32 v3, 0xf0, v3
	v_add3_u32 v2, s38, v2, v3
	ds_read_b128 v[2:5], v2
	v_lshlrev_b32_e32 v128, 13, v6
	v_lshl_add_u64 v[6:7], v[0:1], 0, v[128:129]
	s_waitcnt lgkmcnt(0)
	global_store_dwordx4 v[6:7], v[2:5], off
	v_or_b32_e32 v6, 48, v139
	s_nop 0
	v_lshlrev_b32_e32 v2, 8, v6
	v_add3_u32 v2, s38, v2, v8
	ds_read_b128 v[2:5], v2
	v_lshlrev_b32_e32 v128, 13, v6
	v_lshl_add_u64 v[6:7], v[0:1], 0, v[128:129]
	s_waitcnt lgkmcnt(0)
	global_store_dwordx4 v[6:7], v[2:5], off
	s_nop 1
	v_bitop3_b32 v3, v139, v138, 52 bitop3:0x36
	v_or_b32_e32 v6, 52, v139
	v_lshlrev_b32_e32 v3, 4, v3
	v_lshlrev_b32_e32 v2, 8, v6
	v_and_b32_e32 v3, 0xf0, v3
	v_add3_u32 v2, s38, v2, v3
	ds_read_b128 v[2:5], v2
	v_lshlrev_b32_e32 v128, 13, v6
	v_lshl_add_u64 v[6:7], v[0:1], 0, v[128:129]
	s_waitcnt lgkmcnt(0)
	global_store_dwordx4 v[6:7], v[2:5], off
	s_nop 1
	v_bitop3_b32 v3, v139, v138, 56 bitop3:0x36
	v_or_b32_e32 v6, 56, v139
	v_lshlrev_b32_e32 v3, 4, v3
	v_lshlrev_b32_e32 v2, 8, v6
	v_and_b32_e32 v3, 0xf0, v3
	v_add3_u32 v2, s38, v2, v3
	ds_read_b128 v[2:5], v2
	v_lshlrev_b32_e32 v128, 13, v6
	v_lshl_add_u64 v[6:7], v[0:1], 0, v[128:129]
	s_waitcnt lgkmcnt(0)
	global_store_dwordx4 v[6:7], v[2:5], off
	s_nop 1
	v_bitop3_b32 v4, v139, v138, 60 bitop3:0x36
	v_or_b32_e32 v3, 60, v139
	v_lshlrev_b32_e32 v4, 4, v4
	v_lshlrev_b32_e32 v2, 8, v3
	v_and_b32_e32 v4, 0xf0, v4
	v_add3_u32 v2, s38, v2, v4
	v_lshlrev_b32_e32 v128, 12, v3
	s_branch .LBB0_803

.LBB0_1075:
	s_add_i32 s9, s8, 0xfffe8000
	s_and_b32 s10, s8, 0x18000
	s_waitcnt vmcnt(8)
	s_barrier
	s_and_b32 s9, s9, 0x18000
	s_add_i32 s10, s7, s10
	v_add_u32_e32 v128, s9, v139
	v_or_b32_e32 v141, s9, v140
	s_add_i32 s15, s10, 0x400
	s_add_i32 s11, s10, 0x800
	s_add_i32 s9, s10, 0xc00
	s_add_i32 s8, s8, 0x8000
	s_cmp_eq_u32 s8, 0x100000
	ds_read_b128 v[174:177], v128
	ds_read_b128 v[142:145], v141
	ds_read_b128 v[158:161], v141 offset:1024
	ds_read_b128 v[162:165], v141 offset:2048
	ds_read_b128 v[166:169], v141 offset:3072
	ds_read_b128 v[178:181], v128 offset:1024
	ds_read_b128 v[182:185], v128 offset:2048
	ds_read_b128 v[186:189], v128 offset:3072
	s_waitcnt lgkmcnt(6)
	v_mfma_f32_16x16x32_bf16 v[124:127], v[142:145], v[174:177], v[124:127]
	s_waitcnt lgkmcnt(5)
	v_mfma_f32_16x16x32_bf16 v[120:123], v[158:161], v[174:177], v[120:123]
	s_waitcnt lgkmcnt(4)
	v_mfma_f32_16x16x32_bf16 v[116:119], v[162:165], v[174:177], v[116:119]
	s_waitcnt lgkmcnt(3)
	s_mov_b32 m0, s10
	v_mfma_f32_16x16x32_bf16 v[112:115], v[166:169], v[174:177], v[112:115]
	global_load_lds_dwordx4 v[136:137], off
	v_lshl_add_u64 v[136:137], v[136:137], 0, 64
	s_waitcnt lgkmcnt(2)
	v_mfma_f32_16x16x32_bf16 v[108:111], v[142:145], v[178:181], v[108:111]
	ds_read_b128 v[174:177], v128 offset:4096
	v_mfma_f32_16x16x32_bf16 v[104:107], v[158:161], v[178:181], v[104:107]
	v_mfma_f32_16x16x32_bf16 v[100:103], v[162:165], v[178:181], v[100:103]
	s_mov_b32 m0, s15
	v_mfma_f32_16x16x32_bf16 v[96:99], v[166:169], v[178:181], v[96:99]
	global_load_lds_dwordx4 v[134:135], off
	v_lshl_add_u64 v[134:135], v[134:135], 0, 64
	s_waitcnt lgkmcnt(2)
	v_mfma_f32_16x16x32_bf16 v[92:95], v[142:145], v[182:185], v[92:95]
	ds_read_b128 v[178:181], v128 offset:5120
	v_mfma_f32_16x16x32_bf16 v[88:91], v[158:161], v[182:185], v[88:91]
	v_mfma_f32_16x16x32_bf16 v[84:87], v[162:165], v[182:185], v[84:87]
	s_mov_b32 m0, s11
	v_mfma_f32_16x16x32_bf16 v[80:83], v[166:169], v[182:185], v[80:83]
	global_load_lds_dwordx4 v[132:133], off
	v_lshl_add_u64 v[132:133], v[132:133], 0, 64
	s_waitcnt lgkmcnt(2)
	v_mfma_f32_16x16x32_bf16 v[76:79], v[142:145], v[186:189], v[76:79]
	ds_read_b128 v[182:185], v128 offset:6144
	v_mfma_f32_16x16x32_bf16 v[72:75], v[158:161], v[186:189], v[72:75]
	v_mfma_f32_16x16x32_bf16 v[68:71], v[162:165], v[186:189], v[68:71]
	s_mov_b32 m0, s9
	v_mfma_f32_16x16x32_bf16 v[64:67], v[166:169], v[186:189], v[64:67]
	global_load_lds_dwordx4 v[130:131], off
	v_lshl_add_u64 v[130:131], v[130:131], 0, 64
	s_waitcnt lgkmcnt(2)
	v_mfma_f32_16x16x32_bf16 v[60:63], v[142:145], v[174:177], v[60:63]
	ds_read_b128 v[186:189], v128 offset:7168
	v_mfma_f32_16x16x32_bf16 v[56:59], v[158:161], v[174:177], v[56:59]
	v_mfma_f32_16x16x32_bf16 v[52:55], v[162:165], v[174:177], v[52:55]
	v_mfma_f32_16x16x32_bf16 v[48:51], v[166:169], v[174:177], v[48:51]
	s_waitcnt lgkmcnt(2)
	v_mfma_f32_16x16x32_bf16 v[44:47], v[142:145], v[178:181], v[44:47]
	v_mfma_f32_16x16x32_bf16 v[40:43], v[158:161], v[178:181], v[40:43]
	v_mfma_f32_16x16x32_bf16 v[36:39], v[162:165], v[178:181], v[36:39]
	v_mfma_f32_16x16x32_bf16 v[32:35], v[166:169], v[178:181], v[32:35]
	s_waitcnt lgkmcnt(1)
	v_mfma_f32_16x16x32_bf16 v[28:31], v[142:145], v[182:185], v[28:31]
	v_mfma_f32_16x16x32_bf16 v[24:27], v[158:161], v[182:185], v[24:27]
	v_mfma_f32_16x16x32_bf16 v[20:23], v[162:165], v[182:185], v[20:23]
	v_mfma_f32_16x16x32_bf16 v[16:19], v[166:169], v[182:185], v[16:19]
	s_waitcnt lgkmcnt(0)
	v_mfma_f32_16x16x32_bf16 v[12:15], v[142:145], v[186:189], v[12:15]
	v_mfma_f32_16x16x32_bf16 v[8:11], v[158:161], v[186:189], v[8:11]
	v_mfma_f32_16x16x32_bf16 v[4:7], v[162:165], v[186:189], v[4:7]
	v_mfma_f32_16x16x32_bf16 v[0:3], v[166:169], v[186:189], v[0:3]
	s_cbranch_scc0 .LBB0_1075
	s_waitcnt vmcnt(8)
	s_barrier
	v_add_u32_e32 v128, 0x8000, v139
	v_or_b32_e32 v141, 0x8000, v140
	ds_read_b128 v[130:133], v141
	ds_read_b128 v[134:137], v141 offset:1024
	ds_read_b128 v[142:145], v141 offset:2048
	ds_read_b128 v[158:161], v141 offset:3072
	ds_read_b128 v[162:165], v128
	ds_read_b128 v[166:169], v128 offset:1024
	ds_read_b128 v[174:177], v128 offset:2048
	ds_read_b128 v[178:181], v128 offset:3072
	s_lshl_b32 s8, s6, 8
	s_waitcnt lgkmcnt(0)
	s_and_b32 s15, s8, 0xffffc000
	v_mfma_f32_16x16x32_bf16 v[124:127], v[130:133], v[162:165], v[124:127]
	s_ashr_i32 s7, s6, 1
	s_and_b32 s7, s7, 0xffffff80
	s_and_b32 s6, s6, 0xc0
	v_mfma_f32_16x16x32_bf16 v[120:123], v[134:137], v[162:165], v[120:123]
	s_add_i32 s8, s4, s7
	s_or_b32 s4, s5, s6
	s_ashr_i32 s10, s4, 6
	v_mfma_f32_16x16x32_bf16 v[182:185], v[142:145], v[162:165], v[116:119]
	s_ashr_i32 s11, s10, 31
	v_mfma_f32_16x16x32_bf16 v[112:115], v[158:161], v[162:165], v[112:115]
	v_mfma_f32_16x16x32_bf16 v[108:111], v[130:133], v[166:169], v[108:111]
	v_mfma_f32_16x16x32_bf16 v[104:107], v[134:137], v[166:169], v[104:107]
	v_mfma_f32_16x16x32_bf16 v[100:103], v[142:145], v[166:169], v[100:103]
	v_mfma_f32_16x16x32_bf16 v[96:99], v[158:161], v[166:169], v[96:99]
	v_mfma_f32_16x16x32_bf16 v[92:95], v[130:133], v[174:177], v[92:95]
	v_mfma_f32_16x16x32_bf16 v[88:91], v[134:137], v[174:177], v[88:91]
	v_mfma_f32_16x16x32_bf16 v[84:87], v[142:145], v[174:177], v[84:87]
	v_mfma_f32_16x16x32_bf16 v[80:83], v[158:161], v[174:177], v[80:83]
	ds_read_b128 v[116:119], v128 offset:4096
	ds_read_b128 v[162:165], v128 offset:5120
	ds_read_b128 v[166:169], v128 offset:6144
	ds_read_b128 v[174:177], v128 offset:7168
	s_waitcnt lgkmcnt(0)
	s_waitcnt vmcnt(4)
	s_barrier
	v_mfma_f32_16x16x32_bf16 v[76:79], v[130:133], v[178:181], v[76:79]
	v_mfma_f32_16x16x32_bf16 v[72:75], v[134:137], v[178:181], v[72:75]
	v_mfma_f32_16x16x32_bf16 v[68:71], v[142:145], v[178:181], v[68:71]
	v_mfma_f32_16x16x32_bf16 v[64:67], v[158:161], v[178:181], v[64:67]
	v_mfma_f32_16x16x32_bf16 v[60:63], v[130:133], v[116:119], v[60:63]
	v_mfma_f32_16x16x32_bf16 v[56:59], v[134:137], v[116:119], v[56:59]
	v_mfma_f32_16x16x32_bf16 v[52:55], v[142:145], v[116:119], v[52:55]
	v_mfma_f32_16x16x32_bf16 v[48:51], v[158:161], v[116:119], v[48:51]
	v_add_u32_e32 v117, 0x10000, v139
	v_or_b32_e32 v119, 0x10000, v140
	v_and_b32_e32 v116, 15, v138
	v_mfma_f32_16x16x32_bf16 v[44:47], v[130:133], v[162:165], v[44:47]
	v_and_b32_e32 v118, 63, v138
	v_mfma_f32_16x16x32_bf16 v[40:43], v[134:137], v[162:165], v[40:43]
	v_mfma_f32_16x16x32_bf16 v[36:39], v[142:145], v[162:165], v[36:39]
	v_mfma_f32_16x16x32_bf16 v[32:35], v[158:161], v[162:165], v[32:35]
	v_mfma_f32_16x16x32_bf16 v[28:31], v[130:133], v[166:169], v[28:31]
	v_mfma_f32_16x16x32_bf16 v[24:27], v[134:137], v[166:169], v[24:27]
	v_mfma_f32_16x16x32_bf16 v[20:23], v[142:145], v[166:169], v[20:23]
	v_mfma_f32_16x16x32_bf16 v[16:19], v[158:161], v[166:169], v[16:19]
	v_mfma_f32_16x16x32_bf16 v[12:15], v[130:133], v[174:177], v[12:15]
	v_mfma_f32_16x16x32_bf16 v[8:11], v[134:137], v[174:177], v[8:11]
	v_mfma_f32_16x16x32_bf16 v[4:7], v[142:145], v[174:177], v[4:7]
	v_mfma_f32_16x16x32_bf16 v[0:3], v[158:161], v[174:177], v[0:3]
	ds_read_b128 v[130:133], v119
	ds_read_b128 v[134:137], v119 offset:1024
	ds_read_b128 v[142:145], v119 offset:2048
	ds_read_b128 v[158:161], v119 offset:3072
	ds_read_b128 v[162:165], v117
	ds_read_b128 v[166:169], v117 offset:1024
	ds_read_b128 v[174:177], v117 offset:2048
	ds_read_b128 v[178:181], v117 offset:3072
	v_or_b32_e32 v119, 0x18000, v140
	s_waitcnt lgkmcnt(0)
	s_nop 0
	v_mfma_f32_16x16x32_bf16 v[124:127], v[130:133], v[162:165], v[124:127]
	v_mfma_f32_16x16x32_bf16 v[120:123], v[134:137], v[162:165], v[120:123]
	v_mfma_f32_16x16x32_bf16 v[182:185], v[142:145], v[162:165], v[182:185]
	v_mfma_f32_16x16x32_bf16 v[112:115], v[158:161], v[162:165], v[112:115]
	v_mfma_f32_16x16x32_bf16 v[108:111], v[130:133], v[166:169], v[108:111]
	v_mfma_f32_16x16x32_bf16 v[104:107], v[134:137], v[166:169], v[104:107]
	v_mfma_f32_16x16x32_bf16 v[100:103], v[142:145], v[166:169], v[100:103]
	v_mfma_f32_16x16x32_bf16 v[162:165], v[158:161], v[166:169], v[96:99]
	v_mfma_f32_16x16x32_bf16 v[92:95], v[130:133], v[174:177], v[92:95]
	v_mfma_f32_16x16x32_bf16 v[88:91], v[134:137], v[174:177], v[88:91]
	v_mfma_f32_16x16x32_bf16 v[84:87], v[142:145], v[174:177], v[84:87]
	v_mfma_f32_16x16x32_bf16 v[80:83], v[158:161], v[174:177], v[80:83]
	v_mfma_f32_16x16x32_bf16 v[76:79], v[130:133], v[178:181], v[76:79]
	v_mfma_f32_16x16x32_bf16 v[72:75], v[134:137], v[178:181], v[72:75]
	v_mfma_f32_16x16x32_bf16 v[68:71], v[142:145], v[178:181], v[68:71]
	v_mfma_f32_16x16x32_bf16 v[64:67], v[158:161], v[178:181], v[64:67]
	ds_read_b128 v[96:99], v117 offset:4096
	ds_read_b128 v[166:169], v117 offset:5120
	ds_read_b128 v[174:177], v117 offset:6144
	ds_read_b128 v[178:181], v117 offset:7168
	s_waitcnt lgkmcnt(0)
	s_waitcnt vmcnt(0)
	s_barrier
	v_mfma_f32_16x16x32_bf16 v[60:63], v[130:133], v[96:99], v[60:63]
	v_add_u32_e32 v117, 0x18000, v139
	v_mfma_f32_16x16x32_bf16 v[56:59], v[134:137], v[96:99], v[56:59]
	v_mfma_f32_16x16x32_bf16 v[52:55], v[142:145], v[96:99], v[52:55]
	v_mfma_f32_16x16x32_bf16 v[48:51], v[158:161], v[96:99], v[48:51]
	v_mfma_f32_16x16x32_bf16 v[44:47], v[130:133], v[166:169], v[44:47]
	v_mfma_f32_16x16x32_bf16 v[40:43], v[134:137], v[166:169], v[40:43]
	v_mfma_f32_16x16x32_bf16 v[36:39], v[142:145], v[166:169], v[36:39]
	v_mfma_f32_16x16x32_bf16 v[32:35], v[158:161], v[166:169], v[32:35]
	v_mfma_f32_16x16x32_bf16 v[28:31], v[130:133], v[174:177], v[28:31]
	v_mfma_f32_16x16x32_bf16 v[24:27], v[134:137], v[174:177], v[24:27]
	v_mfma_f32_16x16x32_bf16 v[20:23], v[142:145], v[174:177], v[20:23]
	v_mfma_f32_16x16x32_bf16 v[16:19], v[158:161], v[174:177], v[16:19]
	v_mfma_f32_16x16x32_bf16 v[12:15], v[130:133], v[178:181], v[12:15]
	v_mfma_f32_16x16x32_bf16 v[8:11], v[134:137], v[178:181], v[8:11]
	v_mfma_f32_16x16x32_bf16 v[4:7], v[142:145], v[178:181], v[4:7]
	v_mfma_f32_16x16x32_bf16 v[0:3], v[158:161], v[178:181], v[0:3]
	ds_read_b128 v[130:133], v119
	ds_read_b128 v[134:137], v119 offset:1024
	ds_read_b128 v[140:143], v119 offset:2048
	ds_read_b128 v[144:147], v119 offset:3072
	ds_read_b128 v[96:99], v117
	ds_read_b128 v[158:161], v117 offset:1024
	ds_read_b128 v[166:169], v117 offset:2048
	ds_read_b128 v[174:177], v117 offset:3072
	v_and_b32_e32 v119, 7, v138
	s_waitcnt lgkmcnt(0)
	s_nop 0
	v_mfma_f32_16x16x32_bf16 v[124:127], v[130:133], v[96:99], v[124:127]
	v_mfma_f32_16x16x32_bf16 v[178:181], v[134:137], v[96:99], v[120:123]
	v_mfma_f32_16x16x32_bf16 v[182:185], v[140:143], v[96:99], v[182:185]
	s_nop 5
	v_mul_f32_e32 v128, v125, v125
	v_fmac_f32_e32 v128, v124, v124
	v_fmac_f32_e32 v128, v126, v126
	v_mfma_f32_16x16x32_bf16 v[112:115], v[144:147], v[96:99], v[112:115]
	v_cvt_pk_bf16_f32 v124, v124, v125
	v_cvt_pk_bf16_f32 v125, v126, v127
	v_fmac_f32_e32 v128, v127, v127
	v_mfma_f32_16x16x32_bf16 v[108:111], v[130:133], v[158:161], v[108:111]
	v_cvt_pk_bf16_f32 v127, v180, v181
	v_mfma_f32_16x16x32_bf16 v[104:107], v[134:137], v[158:161], v[104:107]
	v_mfma_f32_16x16x32_bf16 v[96:99], v[140:143], v[158:161], v[100:103]
	v_mfma_f32_16x16x32_bf16 v[100:103], v[144:147], v[158:161], v[162:165]
	v_mfma_f32_16x16x32_bf16 v[92:95], v[130:133], v[166:169], v[92:95]
	v_mfma_f32_16x16x32_bf16 v[88:91], v[134:137], v[166:169], v[88:91]
	v_mfma_f32_16x16x32_bf16 v[84:87], v[140:143], v[166:169], v[84:87]
	v_mfma_f32_16x16x32_bf16 v[80:83], v[144:147], v[166:169], v[80:83]
	ds_read_b128 v[120:123], v117 offset:4096
	ds_read_b128 v[158:161], v117 offset:5120
	ds_read_b128 v[162:165], v117 offset:6144
	ds_read_b128 v[166:169], v117 offset:7168
	s_waitcnt lgkmcnt(0)
	v_bfe_u32 v117, v138, 5, 1
	v_mfma_f32_16x16x32_bf16 v[60:63], v[130:133], v[120:123], v[60:63]
	s_barrier
	v_mfma_f32_16x16x32_bf16 v[56:59], v[134:137], v[120:123], v[56:59]
	v_mfma_f32_16x16x32_bf16 v[52:55], v[140:143], v[120:123], v[52:55]
	v_mfma_f32_16x16x32_bf16 v[48:51], v[144:147], v[120:123], v[48:51]
	v_lshrrev_b32_e32 v121, 1, v138
	v_lshlrev_b32_e32 v120, 7, v116
	v_and_b32_e32 v121, 8, v121
	v_or3_b32 v122, s15, v120, v121
	v_and_b32_e32 v121, 64, v172
	v_xor_b32_e32 v120, 16, v172
	v_add_u32_e32 v121, 64, v121
	v_cmp_lt_i32_e32 vcc, v120, v121
	v_xor_b32_e32 v123, 32, v172
	v_mfma_f32_16x16x32_bf16 v[76:79], v[130:133], v[174:177], v[76:79]
	v_cndmask_b32_e32 v120, v172, v120, vcc
	v_cmp_lt_i32_e32 vcc, v123, v121
	v_lshlrev_b32_e32 v120, 2, v120
	v_mfma_f32_16x16x32_bf16 v[44:47], v[130:133], v[158:161], v[44:47]
	v_cndmask_b32_e32 v121, v172, v123, vcc
	v_bitop3_b32 v123, v117, v138, 7 bitop3:0x78
	v_lshlrev_b32_e32 v123, 4, v123
	v_or_b32_e32 v126, v122, v123
	s_waitcnt vmcnt(0)
	ds_write_b64 v126, v[124:125]
	v_mul_f32_e32 v124, v179, v179
	v_fmac_f32_e32 v124, v178, v178
	v_fmac_f32_e32 v124, v180, v180
	v_bitop3_b32 v125, v117, v119, 2 bitop3:0x36
	v_fmac_f32_e32 v124, v181, v181
	v_lshlrev_b32_e32 v125, 4, v125
	v_add_f32_e32 v124, v128, v124
	v_cvt_pk_bf16_f32 v126, v178, v179
	v_or_b32_e32 v128, v122, v125
	ds_write_b64 v128, v[126:127]
	v_mul_f32_e32 v126, v183, v183
	v_fmac_f32_e32 v126, v182, v182
	v_fmac_f32_e32 v126, v184, v184
	v_fmac_f32_e32 v126, v185, v185
	v_add_f32_e32 v128, v124, v126
	v_bitop3_b32 v124, v117, v119, 4 bitop3:0x36
	v_lshlrev_b32_e32 v124, 4, v124
	v_mfma_f32_16x16x32_bf16 v[28:31], v[130:133], v[162:165], v[28:31]
	v_cvt_pk_bf16_f32 v126, v182, v183
	v_cvt_pk_bf16_f32 v127, v184, v185
	v_lshlrev_b32_e32 v121, 2, v121
	v_mfma_f32_16x16x32_bf16 v[12:15], v[130:133], v[166:169], v[12:15]
	v_or_b32_e32 v130, v122, v124
	ds_write_b64 v130, v[126:127]
	v_mul_f32_e32 v126, v113, v113
	v_fmac_f32_e32 v126, v112, v112
	v_fmac_f32_e32 v126, v114, v114
	v_fmac_f32_e32 v126, v115, v115
	v_add_f32_e32 v128, v128, v126
	v_cvt_pk_bf16_f32 v126, v112, v113
	v_bitop3_b32 v112, v117, v119, 6 bitop3:0x36
	v_lshlrev_b32_e32 v112, 4, v112
	v_cvt_pk_bf16_f32 v127, v114, v115
	v_or_b32_e32 v113, v122, v112
	ds_write_b64 v113, v[126:127]
	ds_bpermute_b32 v113, v120, v128
	v_mfma_f32_16x16x32_bf16 v[72:75], v[134:137], v[174:177], v[72:75]
	v_cmp_gt_u32_e32 vcc, 16, v118
	v_or_b32_e32 v116, s8, v116
	s_waitcnt lgkmcnt(0)
	v_add_f32_e32 v113, v128, v113
	ds_bpermute_b32 v114, v121, v113
	v_mfma_f32_16x16x32_bf16 v[68:71], v[140:143], v[174:177], v[68:71]
	v_mfma_f32_16x16x32_bf16 v[64:67], v[144:147], v[174:177], v[64:67]
	v_mfma_f32_16x16x32_bf16 v[40:43], v[134:137], v[158:161], v[40:43]
	v_mfma_f32_16x16x32_bf16 v[36:39], v[140:143], v[158:161], v[36:39]
	v_mfma_f32_16x16x32_bf16 v[32:35], v[144:147], v[158:161], v[32:35]
	v_mfma_f32_16x16x32_bf16 v[24:27], v[134:137], v[162:165], v[24:27]
	v_mfma_f32_16x16x32_bf16 v[20:23], v[140:143], v[162:165], v[20:23]
	v_mfma_f32_16x16x32_bf16 v[16:19], v[144:147], v[162:165], v[16:19]
	v_mfma_f32_16x16x32_bf16 v[8:11], v[134:137], v[166:169], v[8:11]
	v_mfma_f32_16x16x32_bf16 v[4:7], v[140:143], v[166:169], v[4:7]
	v_mfma_f32_16x16x32_bf16 v[0:3], v[144:147], v[166:169], v[0:3]
	s_and_saveexec_b64 s[6:7], vcc
	s_cbranch_execz .LBB0_1078
	v_ashrrev_i32_e32 v117, 31, v116
	s_waitcnt lgkmcnt(0)
	v_add_f32_e32 v113, v113, v114
	v_lshlrev_b64 v[114:115], 6, v[116:117]
	v_lshl_add_u64 v[114:115], s[64:65], 0, v[114:115]
	v_lshl_add_u64 v[114:115], s[10:11], 2, v[114:115]
	global_store_dword v[114:115], v113, off
